# phase 8 K-loop with empty MMA slots removed (4 barriers per K-tile), EpiDiag and EpiRes epilogue loads batched
# speedup vs baseline: 1.0518x; 1.0193x over previous
; #define PG8_STAGE(bufoff, gbase, voff) do { _Pragma("unroll") for (int _i = 0; _i < 2; ++_i) \
;         __builtin_amdgcn_global_load_lds((const unsigned*)((const char*)(gbase) + (voff)[_i]), (LAS unsigned*)(lds + (bufoff) + ldsw + _i * 8192), 16, 0, 0); } while (0)
; #define PG8_LDA(dst, b, h) do { _Pragma("unroll") for (int m = 0; m < 4; ++m) _Pragma("unroll") for (int k = 0; k < 2; ++k) dst[m][k] = *(const LAS bf16x8*)(lds + PG8_SA(b, h) + aoff + m * 2048 + k * 1024); } while (0)
; #define PG8_LDB(dst, b, h) do { _Pragma("unroll") for (int n = 0; n < 2; ++n) _Pragma("unroll") for (int k = 0; k < 2; ++k) dst[n][k] = *(const LAS bf16x8*)(lds + PG8_SB(b, h) + boff + n * 2048 + k * 1024); } while (0)
; #define PG8_WAIT_V(n) asm volatile("s_waitcnt vmcnt(" #n ")" ::: "memory")
; #define PG8_WAIT_L(n) asm volatile("s_waitcnt lgkmcnt(" #n ")" ::: "memory")
; #define PG8_BAR __builtin_amdgcn_s_barrier()
; #define PG8_SCHED __builtin_amdgcn_sched_barrier(0)
; template <class Epi, class Sched>
; __device__ __forceinline__ void gemm_phase(LAS unsigned char* lds, const Gemm g, const Sched& S, const Epi& E) {
;     ...
;         for (int t = 0; t < nt; t += 2) {
;             const bool last = (t == nt - 2);
;             const char* a1 = cA + (size_t)(t + 1) * kstep;
;             const char* a2 = last ? nA : cA + (size_t)(t + 2) * kstep; const char* b2 = last ? nB : cB + (size_t)(t + 2) * kstep;
;             const char* a3 = a2 + kstep; const char* b3 = b2 + kstep;
;             PG8_LDB(B0, 0, 0); PG8_SCHED; PG8_LDA(At, 0, 0); PG8_STAGE(PG8_SA(1, 1), a1 + hstepA, voffA);
;             PG8_WAIT_L(8); PG8_BAR; PG8_WAIT_L(0); PG8_MMA(0, 0, At, B0); PG8_BAR; PG8_SCHED;
;             PG8_LDB(B1, 0, 1); PG8_STAGE(PG8_SB(0, 0), b2, voffB);
;             PG8_BAR; PG8_WAIT_L(0); if constexpr (!Epi::DIAG) PG8_MMA(0, 1, At, B1); PG8_BAR;
;             PG8_LDA(At, 0, 1); PG8_STAGE(PG8_SA(0, 0), a2, voffA);
;             PG8_BAR; PG8_WAIT_L(0); if constexpr (!Epi::DIAG) PG8_MMA(1, 0, At, B0); PG8_BAR; PG8_SCHED;
;             PG8_STAGE(PG8_SB(0, 1), b2 + hstepB, voffB);
;             PG8_WAIT_V(6); PG8_BAR; PG8_MMA(1, 1, At, B1); PG8_BAR;
;             PG8_LDB(B0, 1, 0); PG8_SCHED; PG8_LDA(At, 1, 0); PG8_STAGE(PG8_SA(0, 1), a2 + hstepA, voffA);
;             PG8_WAIT_L(8); PG8_BAR; PG8_WAIT_L(0); PG8_MMA(0, 0, At, B0); PG8_BAR; PG8_SCHED;
.LBB0_1385:
	ds_read_b128 v[80:83], v91
	ds_read_b128 v[94:97], v91 offset:1024
	ds_read_b128 v[98:101], v91 offset:2048
	ds_read_b128 v[102:105], v91 offset:3072
	s_add_u32 s55, s26, 0xfffff880
	s_addc_u32 s56, s27, -1
	s_cmp_eq_u32 s54, 12
	s_cselect_b32 s57, s19, s56
	s_cselect_b32 s56, s52, s55
	s_cselect_b32 s59, s17, s29
	s_cselect_b32 s58, s53, s28
	ds_read_b128 v[106:109], v92
	ds_read_b128 v[110:113], v92 offset:1024
	ds_read_b128 v[114:117], v92 offset:2048
	ds_read_b128 v[118:121], v92 offset:3072
	ds_read_b128 v[122:125], v92 offset:4096
	ds_read_b128 v[126:129], v92 offset:5120
	ds_read_b128 v[130:133], v92 offset:6144
	ds_read_b128 v[134:137], v92 offset:7168
	s_add_u32 s60, s28, 0x780
	s_addc_u32 s61, s29, 0
	v_lshl_add_u64 v[84:85], s[60:61], 0, v[66:67]
	s_add_i32 m0, s36, 0x1c000
	s_nop 0
	global_load_lds_dwordx4 v[84:85], off
	v_lshl_add_u64 v[84:85], s[60:61], 0, v[70:71]
	s_add_i32 m0, s36, 0x1e000
	s_nop 0
	global_load_lds_dwordx4 v[84:85], off
	v_lshl_add_u64 v[84:85], s[26:27], 0, v[74:75]
	s_add_i32 m0, s25, 0xc000
	s_nop 0
	global_load_lds_dwordx4 v[84:85], off
	v_lshl_add_u64 v[84:85], s[26:27], 0, v[72:73]
	s_add_i32 m0, s25, 0xe000
	s_nop 0
	global_load_lds_dwordx4 v[84:85], off
	s_waitcnt vmcnt(8)
	s_waitcnt lgkmcnt(0)
	s_barrier
	s_setprio 1
	v_mfma_f32_16x16x32_bf16 v[60:63], v[80:83], v[106:109], v[60:63]
	v_mfma_f32_16x16x32_bf16 v[56:59], v[98:101], v[106:109], v[56:59]
	v_mfma_f32_16x16x32_bf16 v[44:47], v[80:83], v[114:117], v[44:47]
	v_mfma_f32_16x16x32_bf16 v[40:43], v[98:101], v[114:117], v[40:43]
	v_mfma_f32_16x16x32_bf16 v[28:31], v[80:83], v[122:125], v[28:31]
	v_mfma_f32_16x16x32_bf16 v[20:23], v[98:101], v[122:125], v[20:23]
	v_mfma_f32_16x16x32_bf16 v[12:15], v[80:83], v[130:133], v[12:15]
	v_mfma_f32_16x16x32_bf16 v[4:7], v[98:101], v[130:133], v[4:7]
	v_mfma_f32_16x16x32_bf16 v[60:63], v[94:97], v[110:113], v[60:63]
	v_mfma_f32_16x16x32_bf16 v[56:59], v[102:105], v[110:113], v[56:59]
	v_mfma_f32_16x16x32_bf16 v[44:47], v[94:97], v[118:121], v[44:47]
	v_mfma_f32_16x16x32_bf16 v[40:43], v[102:105], v[118:121], v[40:43]
	v_mfma_f32_16x16x32_bf16 v[28:31], v[94:97], v[126:129], v[28:31]
	v_mfma_f32_16x16x32_bf16 v[20:23], v[102:105], v[126:129], v[20:23]
	v_mfma_f32_16x16x32_bf16 v[12:15], v[94:97], v[134:137], v[12:15]
	v_mfma_f32_16x16x32_bf16 v[4:7], v[102:105], v[134:137], v[4:7]
	s_setprio 0
	s_barrier
	ds_read_b128 v[80:83], v93
	ds_read_b128 v[94:97], v93 offset:1024
	ds_read_b128 v[98:101], v93 offset:2048
	ds_read_b128 v[102:105], v93 offset:3072
	ds_read_b128 v[106:109], v92 offset:16384
	ds_read_b128 v[110:113], v92 offset:17408
	ds_read_b128 v[114:117], v92 offset:18432
	ds_read_b128 v[118:121], v92 offset:19456
	ds_read_b128 v[122:125], v92 offset:20480
	ds_read_b128 v[126:129], v92 offset:21504
	ds_read_b128 v[130:133], v92 offset:22528
	ds_read_b128 v[134:137], v92 offset:23552
	s_add_i32 s55, s47, s36
	v_lshl_add_u64 v[84:85], s[58:59], 0, v[66:67]
	s_mov_b32 m0, s55
	s_nop 0
	global_load_lds_dwordx4 v[84:85], off
	v_lshl_add_u64 v[138:139], s[58:59], 0, v[70:71]
	s_add_i32 m0, s55, 0x2000
	s_nop 0
	global_load_lds_dwordx4 v[138:139], off
	v_lshl_add_u64 v[140:141], s[56:57], 0, v[64:65]
	s_mov_b32 m0, s25
	s_nop 0
	global_load_lds_dwordx4 v[140:141], off
	v_lshl_add_u64 v[142:143], s[56:57], 0, v[68:69]
	s_mov_b32 m0, s39
	s_nop 0
	global_load_lds_dwordx4 v[142:143], off
	s_waitcnt vmcnt(8)
	s_waitcnt lgkmcnt(0)
	s_barrier
	s_setprio 1
	v_mfma_f32_16x16x32_bf16 v[52:55], v[80:83], v[106:109], v[52:55]
	v_mfma_f32_16x16x32_bf16 v[48:51], v[98:101], v[106:109], v[48:51]
	v_mfma_f32_16x16x32_bf16 v[36:39], v[80:83], v[114:117], v[36:39]
	v_mfma_f32_16x16x32_bf16 v[32:35], v[98:101], v[114:117], v[32:35]
	v_mfma_f32_16x16x32_bf16 v[24:27], v[80:83], v[122:125], v[24:27]
	v_mfma_f32_16x16x32_bf16 v[16:19], v[98:101], v[122:125], v[16:19]
	v_mfma_f32_16x16x32_bf16 v[8:11], v[80:83], v[130:133], v[8:11]
	v_mfma_f32_16x16x32_bf16 v[0:3], v[98:101], v[130:133], v[0:3]
	v_mfma_f32_16x16x32_bf16 v[52:55], v[94:97], v[110:113], v[52:55]
	v_mfma_f32_16x16x32_bf16 v[48:51], v[102:105], v[110:113], v[48:51]
	v_mfma_f32_16x16x32_bf16 v[36:39], v[94:97], v[118:121], v[36:39]
	v_mfma_f32_16x16x32_bf16 v[32:35], v[102:105], v[118:121], v[32:35]
	v_mfma_f32_16x16x32_bf16 v[24:27], v[94:97], v[126:129], v[24:27]
	v_mfma_f32_16x16x32_bf16 v[16:19], v[102:105], v[126:129], v[16:19]
	v_mfma_f32_16x16x32_bf16 v[8:11], v[94:97], v[134:137], v[8:11]
	v_mfma_f32_16x16x32_bf16 v[0:3], v[102:105], v[134:137], v[0:3]
	s_setprio 0
	s_barrier
	s_add_i32 s55, 0, 0x18000
	v_add_u32_e32 v102, s55, v89
	ds_read_b128 v[80:83], v102
	ds_read_b128 v[94:97], v102 offset:1024
	ds_read_b128 v[98:101], v102 offset:2048
	ds_read_b128 v[102:105], v102 offset:3072
	ds_read_b128 v[106:109], v92 offset:32768
	ds_read_b128 v[110:113], v92 offset:33792
	ds_read_b128 v[114:117], v92 offset:34816
	ds_read_b128 v[118:121], v92 offset:35840
	ds_read_b128 v[122:125], v92 offset:36864
	ds_read_b128 v[126:129], v92 offset:37888
	ds_read_b128 v[130:133], v92 offset:38912
	ds_read_b128 v[134:137], v92 offset:39936
	s_add_i32 s55, s48, s36
	v_lshl_add_u64 v[144:145], v[84:85], 0, s[4:5]
	s_mov_b32 m0, s55
	s_nop 0
	global_load_lds_dwordx4 v[144:145], off
	v_lshl_add_u64 v[144:145], v[138:139], 0, s[4:5]
	s_add_i32 m0, s55, 0x2000
	s_nop 0
	global_load_lds_dwordx4 v[144:145], off
	v_lshl_add_u64 v[144:145], v[140:141], 0, s[4:5]
	s_mov_b32 m0, s40
	s_nop 0
	global_load_lds_dwordx4 v[144:145], off
	v_lshl_add_u64 v[144:145], v[142:143], 0, s[4:5]
	s_mov_b32 m0, s41
	s_nop 0
	global_load_lds_dwordx4 v[144:145], off
	s_waitcnt vmcnt(8)
	s_waitcnt lgkmcnt(0)
	s_barrier
; #define PG8_STAGE(bufoff, gbase, voff) do { _Pragma("unroll") for (int _i = 0; _i < 2; ++_i) \
;         __builtin_amdgcn_global_load_lds((const unsigned*)((const char*)(gbase) + (voff)[_i]), (LAS unsigned*)(lds + (bufoff) + ldsw + _i * 8192), 16, 0, 0); } while (0)
; #define PG8_LDA(dst, b, h) do { _Pragma("unroll") for (int m = 0; m < 4; ++m) _Pragma("unroll") for (int k = 0; k < 2; ++k) dst[m][k] = *(const LAS bf16x8*)(lds + PG8_SA(b, h) + aoff + m * 2048 + k * 1024); } while (0)
; #define PG8_LDB(dst, b, h) do { _Pragma("unroll") for (int n = 0; n < 2; ++n) _Pragma("unroll") for (int k = 0; k < 2; ++k) dst[n][k] = *(const LAS bf16x8*)(lds + PG8_SB(b, h) + boff + n * 2048 + k * 1024); } while (0)
; #define PG8_MMA(ai, bj, At, Bt) do { __builtin_amdgcn_s_setprio(1); _Pragma("unroll") for (int m = 0; m < 4; ++m) _Pragma("unroll") for (int n = 0; n < 2; ++n) _Pragma("unroll") for (int k = 0; k < 2; ++k) \
;         acc[ai][bj][m][n] = __builtin_amdgcn_mfma_f32_16x16x32_bf16(Bt[n][k], At[m][k], acc[ai][bj][m][n], 0, 0, 0); __builtin_amdgcn_s_setprio(0); } while (0)
; template <class Epi, class Sched>
; __device__ __forceinline__ void gemm_phase(LAS unsigned char* lds, const Gemm g, const Sched& S, const Epi& E) {
;     ...
;             PG8_WAIT_V(6); PG8_BAR; PG8_MMA(1, 1, At, B1); PG8_BAR;
;             PG8_LDB(B0, 1, 0); PG8_SCHED; PG8_LDA(At, 1, 0); PG8_STAGE(PG8_SA(0, 1), a2 + hstepA, voffA);
;             PG8_WAIT_L(8); PG8_BAR; PG8_WAIT_L(0); PG8_MMA(0, 0, At, B0); PG8_BAR; PG8_SCHED;
;             PG8_LDB(B1, 1, 1); PG8_STAGE(PG8_SB(1, 0), b3, voffB);
;             PG8_BAR; PG8_WAIT_L(0); if constexpr (!Epi::DIAG) PG8_MMA(0, 1, At, B1); PG8_BAR;
;             PG8_LDA(At, 1, 1); PG8_STAGE(PG8_SA(1, 0), a3, voffA);
;             PG8_BAR; PG8_WAIT_L(0); if constexpr (!Epi::DIAG) PG8_MMA(1, 0, At, B0); PG8_BAR; PG8_SCHED;
;             PG8_STAGE(PG8_SB(1, 1), b3 + hstepB, voffB);
;             PG8_WAIT_V(6); PG8_BAR; PG8_MMA(1, 1, At, B1); PG8_BAR;
;         }
;     __device__ __forceinline__ void operator()(const Acc& acc, const Unit& u, int wr, int wc, int fr, int fq) const {
;     ...
;         for (int m = 0; m < 4; ++m) { const size_t row = (size_t)(row0 + m * 16); const bf16_t* pr = proj + row * NPROJ + col0;
;             float ga[8], gb[8], v[8]; unpack8(*(const u32x4*)(pr + C_GA), ga); unpack8(*(const u32x4*)(pr + C_GB), gb);
	s_setprio 1
	v_mfma_f32_16x16x32_bf16 v[60:63], v[80:83], v[106:109], v[60:63]
	v_mfma_f32_16x16x32_bf16 v[56:59], v[98:101], v[106:109], v[56:59]
	v_mfma_f32_16x16x32_bf16 v[44:47], v[80:83], v[114:117], v[44:47]
	v_mfma_f32_16x16x32_bf16 v[40:43], v[98:101], v[114:117], v[40:43]
	v_mfma_f32_16x16x32_bf16 v[28:31], v[80:83], v[122:125], v[28:31]
	v_mfma_f32_16x16x32_bf16 v[20:23], v[98:101], v[122:125], v[20:23]
	v_mfma_f32_16x16x32_bf16 v[12:15], v[80:83], v[130:133], v[12:15]
	v_mfma_f32_16x16x32_bf16 v[4:7], v[98:101], v[130:133], v[4:7]
	v_mfma_f32_16x16x32_bf16 v[60:63], v[94:97], v[110:113], v[60:63]
	v_mfma_f32_16x16x32_bf16 v[56:59], v[102:105], v[110:113], v[56:59]
	v_mfma_f32_16x16x32_bf16 v[44:47], v[94:97], v[118:121], v[44:47]
	v_mfma_f32_16x16x32_bf16 v[40:43], v[102:105], v[118:121], v[40:43]
	v_mfma_f32_16x16x32_bf16 v[28:31], v[94:97], v[126:129], v[28:31]
	v_mfma_f32_16x16x32_bf16 v[20:23], v[102:105], v[126:129], v[20:23]
	v_mfma_f32_16x16x32_bf16 v[12:15], v[94:97], v[134:137], v[12:15]
	v_mfma_f32_16x16x32_bf16 v[4:7], v[102:105], v[134:137], v[4:7]
	s_setprio 0
	s_barrier
	s_add_i32 s55, 0, 0x1c000
	v_add_u32_e32 v102, s55, v89
	ds_read_b128 v[80:83], v102
	ds_read_b128 v[94:97], v102 offset:1024
	ds_read_b128 v[98:101], v102 offset:2048
	ds_read_b128 v[102:105], v102 offset:3072
	ds_read_b128 v[106:109], v92 offset:49152
	ds_read_b128 v[110:113], v92 offset:50176
	ds_read_b128 v[114:117], v92 offset:51200
	ds_read_b128 v[118:121], v92 offset:52224
	ds_read_b128 v[122:125], v92 offset:53248
	ds_read_b128 v[126:129], v92 offset:54272
	ds_read_b128 v[130:133], v92 offset:55296
	ds_read_b128 v[134:137], v92 offset:56320
	s_add_i32 s55, s36, 0x18000
	v_lshl_add_u64 v[144:145], v[84:85], 0, s[12:13]
	s_mov_b32 m0, s55
	s_nop 0
	global_load_lds_dwordx4 v[144:145], off
	v_lshl_add_u64 v[144:145], v[138:139], 0, s[12:13]
	s_add_i32 m0, s55, 0x2000
	s_nop 0
	global_load_lds_dwordx4 v[144:145], off
	v_lshl_add_u64 v[144:145], v[140:141], 0, s[12:13]
	s_mov_b32 m0, s44
	s_nop 0
	global_load_lds_dwordx4 v[144:145], off
	v_lshl_add_u64 v[144:145], v[142:143], 0, s[12:13]
	s_mov_b32 m0, s45
	s_nop 0
	global_load_lds_dwordx4 v[144:145], off
	s_waitcnt vmcnt(8)
	s_waitcnt lgkmcnt(0)
	s_barrier
	s_setprio 1
	v_mfma_f32_16x16x32_bf16 v[52:55], v[80:83], v[106:109], v[52:55]
	v_mfma_f32_16x16x32_bf16 v[48:51], v[98:101], v[106:109], v[48:51]
	v_mfma_f32_16x16x32_bf16 v[36:39], v[80:83], v[114:117], v[36:39]
	v_mfma_f32_16x16x32_bf16 v[32:35], v[98:101], v[114:117], v[32:35]
	v_mfma_f32_16x16x32_bf16 v[24:27], v[80:83], v[122:125], v[24:27]
	v_mfma_f32_16x16x32_bf16 v[16:19], v[98:101], v[122:125], v[16:19]
	v_mfma_f32_16x16x32_bf16 v[8:11], v[80:83], v[130:133], v[8:11]
	v_mfma_f32_16x16x32_bf16 v[0:3], v[98:101], v[130:133], v[0:3]
	v_mfma_f32_16x16x32_bf16 v[52:55], v[94:97], v[110:113], v[52:55]
	v_mfma_f32_16x16x32_bf16 v[48:51], v[102:105], v[110:113], v[48:51]
	v_mfma_f32_16x16x32_bf16 v[36:39], v[94:97], v[118:121], v[36:39]
	v_mfma_f32_16x16x32_bf16 v[32:35], v[102:105], v[118:121], v[32:35]
	v_mfma_f32_16x16x32_bf16 v[24:27], v[94:97], v[126:129], v[24:27]
	v_mfma_f32_16x16x32_bf16 v[16:19], v[102:105], v[126:129], v[16:19]
	v_mfma_f32_16x16x32_bf16 v[8:11], v[94:97], v[134:137], v[8:11]
	v_mfma_f32_16x16x32_bf16 v[0:3], v[102:105], v[134:137], v[0:3]
	s_setprio 0
	s_add_i32 s54, s54, 2
	s_add_u32 s26, s26, 0x100
	s_addc_u32 s27, s27, 0
	s_add_u32 s28, s28, 0x100
	s_addc_u32 s29, s29, 0
	s_cmp_gt_u32 s54, 13
	s_barrier
	s_cbranch_scc0 .LBB0_1385
	v_lshl_or_b32 v80, s51, 7, v90
	v_lshl_add_u32 v82, s24, 7, v88
	v_ashrrev_i32_e32 v81, 31, v80
	v_mov_b64_e32 v[84:85], s[10:11]
	v_mad_i64_i32 v[94:95], s[26:27], v82, s49, v[84:85]
	v_lshlrev_b64 v[80:81], 1, v[80:81]
	v_lshl_add_u64 v[98:99], v[94:95], 0, v[80:81]
	v_add_co_u32_e32 v94, vcc, 0x2000, v98
	v_ashrrev_i32_e32 v83, 31, v82
	s_nop 0
	v_addc_co_u32_e32 v95, vcc, 0, v99, vcc
	v_add_co_u32_e32 v98, vcc, s50, v98
	global_load_dwordx4 v[94:97], v[94:95], off offset:2048
	s_nop 0
	v_addc_co_u32_e32 v99, vcc, 0, v99, vcc
	global_load_dwordx4 v[98:101], v[98:99], off offset:2048
	v_or_b32_e32 v210, 16, v82
	v_mad_i64_i32 v[212:213], s[26:27], v210, s49, v[84:85]
	v_lshl_add_u64 v[212:213], v[212:213], 0, v[80:81]
	v_add_co_u32_e32 v214, vcc, s42, v212
	s_nop 1
	v_addc_co_u32_e32 v215, vcc, 0, v213, vcc
	v_add_co_u32_e32 v212, vcc, s50, v212
	s_nop 1
	v_addc_co_u32_e32 v213, vcc, 0, v213, vcc
	global_load_dwordx4 v[186:189], v[214:215], off offset:2048
	global_load_dwordx4 v[190:193], v[212:213], off offset:2048
	v_or_b32_e32 v210, 32, v82
	v_mad_i64_i32 v[212:213], s[26:27], v210, s49, v[84:85]
	v_lshl_add_u64 v[212:213], v[212:213], 0, v[80:81]
	v_add_co_u32_e32 v214, vcc, s42, v212
	s_nop 1
	v_addc_co_u32_e32 v215, vcc, 0, v213, vcc
	v_add_co_u32_e32 v212, vcc, s50, v212
	s_nop 1
	v_addc_co_u32_e32 v213, vcc, 0, v213, vcc
	global_load_dwordx4 v[194:197], v[214:215], off offset:2048
	global_load_dwordx4 v[198:201], v[212:213], off offset:2048
	v_or_b32_e32 v210, 48, v82
	v_mad_i64_i32 v[212:213], s[26:27], v210, s49, v[84:85]
	v_lshl_add_u64 v[212:213], v[212:213], 0, v[80:81]
	v_add_co_u32_e32 v214, vcc, s42, v212
	s_nop 1
	v_addc_co_u32_e32 v215, vcc, 0, v213, vcc
	v_add_co_u32_e32 v212, vcc, s50, v212
	s_nop 1
	v_addc_co_u32_e32 v213, vcc, 0, v213, vcc
	global_load_dwordx4 v[202:205], v[214:215], off offset:2048
	global_load_dwordx4 v[206:209], v[212:213], off offset:2048
	s_mov_b32 s51, s16
	s_mov_b32 s24, s18
	s_mov_b64 s[28:29], s[22:23]
	s_waitcnt vmcnt(6)
; __device__ __forceinline__ u32x4 pack8(const float* f) { u32x4 w; w.x = pk2(f[0], f[1]); w.y = pk2(f[2], f[3]); w.z = pk2(f[4], f[5]); w.w = pk2(f[6], f[7]); return w; }
;     __device__ __forceinline__ void operator()(const Acc& acc, const Unit& u, int wr, int wc, int fr, int fq) const {
;     ...
;         for (int m = 0; m < 4; ++m) { const size_t row = (size_t)(row0 + m * 16); const bf16_t* pr = proj + row * NPROJ + col0;
;             float ga[8], gb[8], v[8]; unpack8(*(const u32x4*)(pr + C_GA), ga); unpack8(*(const u32x4*)(pr + C_GB), gb);
; #pragma unroll
;             for (int n = 0; n < 2; ++n) {
;                 const f32x4 A4 = {ga[4 * n], ga[4 * n + 1], ga[4 * n + 2], ga[4 * n + 3]}, B4 = {gb[4 * n], gb[4 * n + 1], gb[4 * n + 2], gb[4 * n + 3]};
;                 const f32x4 aa = A4 * (-1.4426950408889634f), ab = B4 * (-1.4426950408889634f);
;                 f32x4 ta, tb;
; #pragma unroll
;                 for (int j = 0; j < 4; ++j) { ta[j] = __builtin_amdgcn_exp2f(aa[j]); tb[j] = __builtin_amdgcn_exp2f(ab[j]); }
;                 ta = ta + 1.0f; tb = tb + 1.0f;
; #pragma unroll
;                 for (int j = 0; j < 4; ++j) { ta[j] = __builtin_amdgcn_rcpf(ta[j]); tb[j] = __builtin_amdgcn_rcpf(tb[j]); }
;                 const f32x4 r = acc[0][0][m][n] * ta + acc[1][1][m][n] * tb;
; #pragma unroll
;                 for (int j = 0; j < 4; ++j) v[4 * n + j] = r[j]; }
;             *(u32x4*)(O + row * DM + col0) = pack8(v); }
	v_lshlrev_b32_e32 v102, 16, v94
	v_and_b32_e32 v94, 0xffff0000, v94
	v_lshlrev_b32_e32 v103, 16, v95
	v_and_b32_e32 v95, 0xffff0000, v95
	v_lshlrev_b32_e32 v104, 16, v96
	v_and_b32_e32 v96, 0xffff0000, v96
	v_lshlrev_b32_e32 v106, 16, v98
	v_and_b32_e32 v98, 0xffff0000, v98
	v_lshlrev_b32_e32 v105, 16, v97
	v_and_b32_e32 v97, 0xffff0000, v97
	v_lshlrev_b32_e32 v107, 16, v99
	v_and_b32_e32 v99, 0xffff0000, v99
	v_lshlrev_b32_e32 v108, 16, v100
	v_and_b32_e32 v100, 0xffff0000, v100
	v_lshlrev_b32_e32 v109, 16, v101
	v_and_b32_e32 v110, 0xffff0000, v101
	v_mul_f32_e32 v101, 0xbfb8aa3b, v102
	v_mul_f32_e32 v102, 0xbfb8aa3b, v94
	v_mul_f32_e32 v103, 0xbfb8aa3b, v103
	v_mul_f32_e32 v111, 0xbfb8aa3b, v95
	v_mul_f32_e32 v112, 0xbfb8aa3b, v96
	v_mul_f32_e32 v106, 0xbfb8aa3b, v106
	v_mul_f32_e32 v114, 0xbfb8aa3b, v98
	v_mul_f32_e32 v104, 0xbfb8aa3b, v104
	v_mul_f32_e32 v113, 0xbfb8aa3b, v97
	v_exp_f32_e32 v95, v102
	v_exp_f32_e32 v96, v103
	v_mul_f32_e32 v107, 0xbfb8aa3b, v107
	v_exp_f32_e32 v97, v111
	v_mul_f32_e32 v111, 0xbfb8aa3b, v99
	v_mul_f32_e32 v108, 0xbfb8aa3b, v108
	v_exp_f32_e32 v99, v112
	v_mul_f32_e32 v112, 0xbfb8aa3b, v100
	v_exp_f32_e32 v102, v106
	v_exp_f32_e32 v103, v114
	v_mul_f32_e32 v105, 0xbfb8aa3b, v105
	v_exp_f32_e32 v94, v101
	v_exp_f32_e32 v98, v104
	v_mul_f32_e32 v109, 0xbfb8aa3b, v109
	v_mul_f32_e32 v110, 0xbfb8aa3b, v110
	v_exp_f32_e32 v104, v107
	v_exp_f32_e32 v106, v108
	v_exp_f32_e32 v107, v112
	v_exp_f32_e32 v100, v105
	v_exp_f32_e32 v105, v111
	v_exp_f32_e32 v108, v109
	v_exp_f32_e32 v109, v110
	v_exp_f32_e32 v101, v113
	v_pk_add_f32 v[102:103], v[102:103], 1.0 op_sel_hi:[1,0]
	v_pk_add_f32 v[94:95], v[94:95], 1.0 op_sel_hi:[1,0]
	v_pk_add_f32 v[106:107], v[106:107], 1.0 op_sel_hi:[1,0]
	v_rcp_f32_e32 v102, v102
	v_rcp_f32_e32 v103, v103
	v_pk_add_f32 v[98:99], v[98:99], 1.0 op_sel_hi:[1,0]
	v_pk_add_f32 v[104:105], v[104:105], 1.0 op_sel_hi:[1,0]
	v_rcp_f32_e32 v94, v94
	v_rcp_f32_e32 v95, v95
	v_pk_add_f32 v[108:109], v[108:109], 1.0 op_sel_hi:[1,0]
	v_rcp_f32_e32 v106, v106
	v_rcp_f32_e32 v107, v107
	v_pk_add_f32 v[96:97], v[96:97], 1.0 op_sel_hi:[1,0]
	v_pk_add_f32 v[100:101], v[100:101], 1.0 op_sel_hi:[1,0]
	v_rcp_f32_e32 v98, v98
	v_rcp_f32_e32 v99, v99
	v_rcp_f32_e32 v104, v104
	v_rcp_f32_e32 v105, v105
	v_rcp_f32_e32 v108, v108
	v_rcp_f32_e32 v109, v109
	v_rcp_f32_e32 v96, v96
	v_rcp_f32_e32 v97, v97
	v_rcp_f32_e32 v100, v100
	v_rcp_f32_e32 v101, v101
	v_pk_mul_f32 v[52:53], v[52:53], v[102:103]
	v_pk_mul_f32 v[48:49], v[48:49], v[106:107]
	v_pk_fma_f32 v[52:53], v[60:61], v[94:95], v[52:53]
	v_pk_mul_f32 v[54:55], v[54:55], v[104:105]
	v_pk_mul_f32 v[50:51], v[50:51], v[108:109]
	v_pk_fma_f32 v[56:57], v[56:57], v[98:99], v[48:49]
	v_cvt_pk_bf16_f32 v48, v52, v53
	v_lshlrev_b64 v[52:53], 12, v[82:83]
	v_pk_fma_f32 v[54:55], v[62:63], v[96:97], v[54:55]
	v_pk_fma_f32 v[58:59], v[58:59], v[100:101], v[50:51]
	v_lshl_add_u64 v[52:53], s[8:9], 0, v[52:53]
	v_cvt_pk_bf16_f32 v49, v54, v55
	v_cvt_pk_bf16_f32 v50, v56, v57
	v_cvt_pk_bf16_f32 v51, v58, v59
	v_lshl_add_u64 v[52:53], v[52:53], 0, v[80:81]
	v_or_b32_e32 v56, 16, v82
	global_store_dwordx4 v[52:53], v[48:51], off
	v_ashrrev_i32_e32 v57, 31, v56
	s_nop 0
	v_mad_i64_i32 v[48:49], s[26:27], v56, s49, v[84:85]
	v_lshl_add_u64 v[52:53], v[48:49], 0, v[80:81]
	v_add_co_u32_e32 v48, vcc, s42, v52
	s_nop 1
	v_addc_co_u32_e32 v49, vcc, 0, v53, vcc
	v_add_co_u32_e32 v52, vcc, s50, v52
	s_waitcnt vmcnt(5)
	v_mov_b32_e32 v48, v186
	v_mov_b32_e32 v49, v187
	v_mov_b32_e32 v50, v188
	v_mov_b32_e32 v51, v189
	s_nop 0
	v_addc_co_u32_e32 v53, vcc, 0, v53, vcc
	v_mov_b32_e32 v52, v190
	v_mov_b32_e32 v53, v191
	v_mov_b32_e32 v54, v192
	v_mov_b32_e32 v55, v193
	v_lshlrev_b32_e32 v59, 16, v49
	v_and_b32_e32 v49, 0xffff0000, v49
	v_lshlrev_b32_e32 v58, 16, v48
	v_lshlrev_b32_e32 v63, 16, v53
	v_and_b32_e32 v53, 0xffff0000, v53
	v_lshlrev_b32_e32 v62, 16, v52
	v_and_b32_e32 v52, 0xffff0000, v52
	v_lshlrev_b32_e32 v83, 16, v54
	v_and_b32_e32 v54, 0xffff0000, v54
	v_lshlrev_b32_e32 v94, 16, v55
	v_and_b32_e32 v55, 0xffff0000, v55
	v_mul_f32_e32 v63, 0xbfb8aa3b, v63
	v_mul_f32_e32 v97, 0xbfb8aa3b, v53
	v_and_b32_e32 v48, 0xffff0000, v48
	v_lshlrev_b32_e32 v60, 16, v50
	v_and_b32_e32 v50, 0xffff0000, v50
	v_lshlrev_b32_e32 v61, 16, v51
	v_and_b32_e32 v51, 0xffff0000, v51
	v_mul_f32_e32 v62, 0xbfb8aa3b, v62
	v_mul_f32_e32 v52, 0xbfb8aa3b, v52
	v_mul_f32_e32 v59, 0xbfb8aa3b, v59
	v_mul_f32_e32 v96, 0xbfb8aa3b, v49
	v_mul_f32_e32 v99, 0xbfb8aa3b, v54
	v_mul_f32_e32 v102, 0xbfb8aa3b, v55
	v_exp_f32_e32 v54, v63
	v_exp_f32_e32 v55, v97
	v_mul_f32_e32 v58, 0xbfb8aa3b, v58
	v_mul_f32_e32 v95, 0xbfb8aa3b, v48
	v_mul_f32_e32 v98, 0xbfb8aa3b, v50
	v_mul_f32_e32 v101, 0xbfb8aa3b, v51
	v_exp_f32_e32 v50, v62
	v_exp_f32_e32 v51, v52
	v_exp_f32_e32 v52, v59
	v_exp_f32_e32 v53, v96
	v_exp_f32_e32 v48, v58
	v_exp_f32_e32 v49, v95
	v_mul_f32_e32 v60, 0xbfb8aa3b, v60
	v_mul_f32_e32 v83, 0xbfb8aa3b, v83
	v_mul_f32_e32 v100, 0xbfb8aa3b, v61
	v_mul_f32_e32 v94, 0xbfb8aa3b, v94
	v_exp_f32_e32 v58, v60
	v_exp_f32_e32 v60, v83
	v_exp_f32_e32 v61, v99
	v_pk_add_f32 v[54:55], v[54:55], 1.0 op_sel_hi:[1,0]
	v_exp_f32_e32 v59, v98
	v_exp_f32_e32 v94, v94
	v_exp_f32_e32 v95, v102
	v_pk_add_f32 v[52:53], v[52:53], 1.0 op_sel_hi:[1,0]
	v_pk_add_f32 v[50:51], v[50:51], 1.0 op_sel_hi:[1,0]
	v_rcp_f32_e32 v54, v54
	v_rcp_f32_e32 v55, v55
	v_exp_f32_e32 v62, v100
	v_exp_f32_e32 v63, v101
	v_pk_add_f32 v[48:49], v[48:49], 1.0 op_sel_hi:[1,0]
	v_rcp_f32_e32 v50, v50
	v_rcp_f32_e32 v51, v51
	v_rcp_f32_e32 v52, v52
	v_rcp_f32_e32 v53, v53
	v_rcp_f32_e32 v48, v48
	v_rcp_f32_e32 v49, v49
	v_pk_add_f32 v[60:61], v[60:61], 1.0 op_sel_hi:[1,0]
	v_pk_add_f32 v[58:59], v[58:59], 1.0 op_sel_hi:[1,0]
	v_pk_add_f32 v[94:95], v[94:95], 1.0 op_sel_hi:[1,0]
	v_rcp_f32_e32 v60, v60
	v_pk_mul_f32 v[38:39], v[38:39], v[54:55]
	v_rcp_f32_e32 v61, v61
	v_pk_add_f32 v[62:63], v[62:63], 1.0 op_sel_hi:[1,0]
	v_rcp_f32_e32 v58, v58
	v_rcp_f32_e32 v59, v59
	v_pk_mul_f32 v[36:37], v[36:37], v[50:51]
	v_pk_fma_f32 v[38:39], v[46:47], v[52:53], v[38:39]
	v_rcp_f32_e32 v46, v94
	v_rcp_f32_e32 v47, v95
	v_pk_fma_f32 v[36:37], v[44:45], v[48:49], v[36:37]
	v_rcp_f32_e32 v44, v62
	v_rcp_f32_e32 v45, v63
	v_pk_mul_f32 v[32:33], v[32:33], v[60:61]
	s_nop 0
	v_pk_fma_f32 v[40:41], v[40:41], v[58:59], v[32:33]
	v_pk_mul_f32 v[32:33], v[34:35], v[46:47]
	v_cvt_pk_bf16_f32 v34, v40, v41
	v_pk_fma_f32 v[42:43], v[42:43], v[44:45], v[32:33]
	v_cvt_pk_bf16_f32 v32, v36, v37
	v_lshlrev_b64 v[36:37], 12, v[56:57]
	v_lshl_add_u64 v[36:37], s[8:9], 0, v[36:37]
	v_cvt_pk_bf16_f32 v33, v38, v39
	v_cvt_pk_bf16_f32 v35, v42, v43
	v_lshl_add_u64 v[36:37], v[36:37], 0, v[80:81]
	v_or_b32_e32 v40, 32, v82
	global_store_dwordx4 v[36:37], v[32:35], off
	v_ashrrev_i32_e32 v41, 31, v40
	s_nop 0
	v_mad_i64_i32 v[32:33], s[26:27], v40, s49, v[84:85]
	v_lshl_add_u64 v[36:37], v[32:33], 0, v[80:81]
	v_add_co_u32_e32 v32, vcc, s42, v36
	s_nop 1
	v_addc_co_u32_e32 v33, vcc, 0, v37, vcc
	v_add_co_u32_e32 v36, vcc, s50, v36
	s_waitcnt vmcnt(4)
; __device__ __forceinline__ u32x4 pack8(const float* f) { u32x4 w; w.x = pk2(f[0], f[1]); w.y = pk2(f[2], f[3]); w.z = pk2(f[4], f[5]); w.w = pk2(f[6], f[7]); return w; }
;     __device__ __forceinline__ void operator()(const Acc& acc, const Unit& u, int wr, int wc, int fr, int fq) const {
;     ...
;         for (int m = 0; m < 4; ++m) { const size_t row = (size_t)(row0 + m * 16); const bf16_t* pr = proj + row * NPROJ + col0;
;             float ga[8], gb[8], v[8]; unpack8(*(const u32x4*)(pr + C_GA), ga); unpack8(*(const u32x4*)(pr + C_GB), gb);
; #pragma unroll
;             for (int n = 0; n < 2; ++n) {
;                 const f32x4 A4 = {ga[4 * n], ga[4 * n + 1], ga[4 * n + 2], ga[4 * n + 3]}, B4 = {gb[4 * n], gb[4 * n + 1], gb[4 * n + 2], gb[4 * n + 3]};
;                 const f32x4 aa = A4 * (-1.4426950408889634f), ab = B4 * (-1.4426950408889634f);
;                 f32x4 ta, tb;
; #pragma unroll
;                 for (int j = 0; j < 4; ++j) { ta[j] = __builtin_amdgcn_exp2f(aa[j]); tb[j] = __builtin_amdgcn_exp2f(ab[j]); }
;                 ta = ta + 1.0f; tb = tb + 1.0f;
; #pragma unroll
;                 for (int j = 0; j < 4; ++j) { ta[j] = __builtin_amdgcn_rcpf(ta[j]); tb[j] = __builtin_amdgcn_rcpf(tb[j]); }
;                 const f32x4 r = acc[0][0][m][n] * ta + acc[1][1][m][n] * tb;
; #pragma unroll
;                 for (int j = 0; j < 4; ++j) v[4 * n + j] = r[j]; }
;             *(u32x4*)(O + row * DM + col0) = pack8(v); }
	v_mov_b32_e32 v32, v194
	v_mov_b32_e32 v33, v195
	v_mov_b32_e32 v34, v196
	v_mov_b32_e32 v35, v197
	s_nop 0
	v_addc_co_u32_e32 v37, vcc, 0, v37, vcc
	v_mov_b32_e32 v36, v198
	v_mov_b32_e32 v37, v199
	v_mov_b32_e32 v38, v200
	v_mov_b32_e32 v39, v201
	v_lshlrev_b32_e32 v43, 16, v33
	v_and_b32_e32 v33, 0xffff0000, v33
	v_lshlrev_b32_e32 v44, 16, v34
	v_lshlrev_b32_e32 v46, 16, v36
	v_and_b32_e32 v36, 0xffff0000, v36
	v_lshlrev_b32_e32 v47, 16, v37
	v_and_b32_e32 v37, 0xffff0000, v37
	v_and_b32_e32 v34, 0xffff0000, v34
	v_lshlrev_b32_e32 v45, 16, v35
	v_and_b32_e32 v35, 0xffff0000, v35
	v_lshlrev_b32_e32 v48, 16, v38
	v_and_b32_e32 v38, 0xffff0000, v38
	v_lshlrev_b32_e32 v49, 16, v39
	v_and_b32_e32 v39, 0xffff0000, v39
	v_mul_f32_e32 v46, 0xbfb8aa3b, v46
	v_mul_f32_e32 v36, 0xbfb8aa3b, v36
	v_mul_f32_e32 v47, 0xbfb8aa3b, v47
	v_mul_f32_e32 v52, 0xbfb8aa3b, v37
	v_lshlrev_b32_e32 v42, 16, v32
	v_and_b32_e32 v32, 0xffff0000, v32
	v_mul_f32_e32 v43, 0xbfb8aa3b, v43
	v_mul_f32_e32 v51, 0xbfb8aa3b, v33
	v_mul_f32_e32 v53, 0xbfb8aa3b, v34
	v_mul_f32_e32 v54, 0xbfb8aa3b, v38
	v_mul_f32_e32 v55, 0xbfb8aa3b, v35
	v_mul_f32_e32 v56, 0xbfb8aa3b, v39
	v_exp_f32_e32 v34, v46
	v_exp_f32_e32 v35, v36
	v_exp_f32_e32 v38, v47
	v_exp_f32_e32 v39, v52
	v_mul_f32_e32 v42, 0xbfb8aa3b, v42
	v_mul_f32_e32 v50, 0xbfb8aa3b, v32
	v_exp_f32_e32 v36, v43
	v_exp_f32_e32 v37, v51
	v_exp_f32_e32 v32, v42
	v_exp_f32_e32 v33, v50
	v_mul_f32_e32 v44, 0xbfb8aa3b, v44
	v_mul_f32_e32 v48, 0xbfb8aa3b, v48
	v_mul_f32_e32 v45, 0xbfb8aa3b, v45
	v_pk_add_f32 v[38:39], v[38:39], 1.0 op_sel_hi:[1,0]
	v_pk_add_f32 v[34:35], v[34:35], 1.0 op_sel_hi:[1,0]
	v_exp_f32_e32 v42, v44
	v_exp_f32_e32 v44, v48
	v_exp_f32_e32 v46, v45
	v_pk_add_f32 v[36:37], v[36:37], 1.0 op_sel_hi:[1,0]
	v_rcp_f32_e32 v34, v34
	v_rcp_f32_e32 v35, v35
	v_rcp_f32_e32 v38, v38
	v_rcp_f32_e32 v39, v39
	v_exp_f32_e32 v45, v54
	v_mul_f32_e32 v49, 0xbfb8aa3b, v49
	v_exp_f32_e32 v43, v53
	v_pk_add_f32 v[32:33], v[32:33], 1.0 op_sel_hi:[1,0]
	v_rcp_f32_e32 v36, v36
	v_rcp_f32_e32 v37, v37
	v_exp_f32_e32 v48, v49
	v_exp_f32_e32 v49, v56
	v_rcp_f32_e32 v32, v32
	v_rcp_f32_e32 v33, v33
	v_exp_f32_e32 v47, v55
	v_pk_mul_f32 v[24:25], v[24:25], v[34:35]
	v_pk_mul_f32 v[26:27], v[26:27], v[38:39]
	v_pk_add_f32 v[34:35], v[44:45], 1.0 op_sel_hi:[1,0]
	v_pk_fma_f32 v[26:27], v[30:31], v[36:37], v[26:27]
	v_pk_add_f32 v[30:31], v[42:43], 1.0 op_sel_hi:[1,0]
	v_rcp_f32_e32 v34, v34
	v_rcp_f32_e32 v35, v35
	v_pk_fma_f32 v[24:25], v[28:29], v[32:33], v[24:25]
	v_pk_add_f32 v[32:33], v[48:49], 1.0 op_sel_hi:[1,0]
	v_rcp_f32_e32 v30, v30
	v_rcp_f32_e32 v31, v31
	v_pk_add_f32 v[28:29], v[46:47], 1.0 op_sel_hi:[1,0]
	v_rcp_f32_e32 v32, v32
	v_rcp_f32_e32 v33, v33
	v_rcp_f32_e32 v28, v28
	v_rcp_f32_e32 v29, v29
	v_pk_mul_f32 v[16:17], v[16:17], v[34:35]
	s_nop 0
	v_pk_fma_f32 v[20:21], v[20:21], v[30:31], v[16:17]
	v_pk_mul_f32 v[16:17], v[18:19], v[32:33]
	v_cvt_pk_bf16_f32 v18, v20, v21
	v_lshlrev_b64 v[20:21], 12, v[40:41]
	v_pk_fma_f32 v[22:23], v[22:23], v[28:29], v[16:17]
	v_lshl_add_u64 v[20:21], s[8:9], 0, v[20:21]
	v_cvt_pk_bf16_f32 v16, v24, v25
	v_cvt_pk_bf16_f32 v17, v26, v27
	v_cvt_pk_bf16_f32 v19, v22, v23
	v_lshl_add_u64 v[20:21], v[20:21], 0, v[80:81]
	v_or_b32_e32 v24, 48, v82
	global_store_dwordx4 v[20:21], v[16:19], off
	v_ashrrev_i32_e32 v25, 31, v24
	s_nop 0
	v_mad_i64_i32 v[16:17], s[26:27], v24, s49, v[84:85]
	v_lshl_add_u64 v[20:21], v[16:17], 0, v[80:81]
	v_add_co_u32_e32 v16, vcc, s42, v20
	s_mov_b64 s[26:27], s[20:21]
	s_nop 0
	v_addc_co_u32_e32 v17, vcc, 0, v21, vcc
	v_add_co_u32_e32 v20, vcc, s50, v20
	s_waitcnt vmcnt(3)
	v_mov_b32_e32 v16, v202
	v_mov_b32_e32 v17, v203
	v_mov_b32_e32 v18, v204
	v_mov_b32_e32 v19, v205
	s_nop 0
	v_addc_co_u32_e32 v21, vcc, 0, v21, vcc
	v_mov_b32_e32 v20, v206
	v_mov_b32_e32 v21, v207
	v_mov_b32_e32 v22, v208
	v_mov_b32_e32 v23, v209
	s_and_b64 vcc, exec, s[6:7]
	v_lshlrev_b32_e32 v29, 16, v19
	v_and_b32_e32 v30, 0xffff0000, v19
	v_lshlrev_b32_e32 v26, 16, v16
	v_lshlrev_b32_e32 v19, 16, v20
	v_and_b32_e32 v20, 0xffff0000, v20
	v_and_b32_e32 v16, 0xffff0000, v16
	v_lshlrev_b32_e32 v28, 16, v18
	v_and_b32_e32 v18, 0xffff0000, v18
	v_lshlrev_b32_e32 v31, 16, v21
	v_and_b32_e32 v21, 0xffff0000, v21
	v_mul_f32_e32 v19, 0xbfb8aa3b, v19
	v_mul_f32_e32 v20, 0xbfb8aa3b, v20
	v_lshlrev_b32_e32 v27, 16, v17
	v_and_b32_e32 v17, 0xffff0000, v17
	v_lshlrev_b32_e32 v32, 16, v22
	v_and_b32_e32 v22, 0xffff0000, v22
	v_lshlrev_b32_e32 v33, 16, v23
	v_and_b32_e32 v34, 0xffff0000, v23
	v_mul_f32_e32 v23, 0xbfb8aa3b, v26
	v_mul_f32_e32 v26, 0xbfb8aa3b, v16
	v_mul_f32_e32 v31, 0xbfb8aa3b, v31
	v_mul_f32_e32 v36, 0xbfb8aa3b, v21
	v_mul_f32_e32 v37, 0xbfb8aa3b, v18
	v_exp_f32_e32 v18, v19
	v_exp_f32_e32 v19, v20
	v_mul_f32_e32 v27, 0xbfb8aa3b, v27
	v_mul_f32_e32 v35, 0xbfb8aa3b, v17
	v_mul_f32_e32 v38, 0xbfb8aa3b, v22
	v_exp_f32_e32 v16, v23
	v_exp_f32_e32 v17, v26
	v_exp_f32_e32 v22, v31
	v_exp_f32_e32 v23, v36
	v_exp_f32_e32 v20, v27
	v_exp_f32_e32 v21, v35
	v_pk_add_f32 v[18:19], v[18:19], 1.0 op_sel_hi:[1,0]
	v_pk_add_f32 v[16:17], v[16:17], 1.0 op_sel_hi:[1,0]
	v_pk_add_f32 v[22:23], v[22:23], 1.0 op_sel_hi:[1,0]
	v_rcp_f32_e32 v18, v18
	v_rcp_f32_e32 v19, v19
	v_pk_add_f32 v[20:21], v[20:21], 1.0 op_sel_hi:[1,0]
	v_rcp_f32_e32 v16, v16
	v_rcp_f32_e32 v17, v17
	v_rcp_f32_e32 v22, v22
	v_rcp_f32_e32 v23, v23
	v_rcp_f32_e32 v20, v20
	v_rcp_f32_e32 v21, v21
	v_mul_f32_e32 v28, 0xbfb8aa3b, v28
	v_mul_f32_e32 v32, 0xbfb8aa3b, v32
	v_pk_mul_f32 v[8:9], v[8:9], v[18:19]
	v_exp_f32_e32 v26, v28
	v_exp_f32_e32 v28, v32
	v_pk_mul_f32 v[10:11], v[10:11], v[22:23]
	v_pk_fma_f32 v[8:9], v[12:13], v[16:17], v[8:9]
	v_mul_f32_e32 v12, 0xbfb8aa3b, v29
	v_exp_f32_e32 v29, v38
	v_exp_f32_e32 v27, v37
	v_pk_fma_f32 v[10:11], v[14:15], v[20:21], v[10:11]
	v_mul_f32_e32 v13, 0xbfb8aa3b, v33
	v_mul_f32_e32 v15, 0xbfb8aa3b, v34
	v_exp_f32_e32 v14, v13
	v_mul_f32_e32 v13, 0xbfb8aa3b, v30
	v_exp_f32_e32 v15, v15
	v_exp_f32_e32 v12, v12
	v_exp_f32_e32 v13, v13
	v_pk_add_f32 v[18:19], v[28:29], 1.0 op_sel_hi:[1,0]
	v_pk_add_f32 v[16:17], v[26:27], 1.0 op_sel_hi:[1,0]
	v_rcp_f32_e32 v18, v18
	v_rcp_f32_e32 v19, v19
	v_pk_add_f32 v[14:15], v[14:15], 1.0 op_sel_hi:[1,0]
	v_rcp_f32_e32 v16, v16
	v_rcp_f32_e32 v17, v17
	v_pk_add_f32 v[12:13], v[12:13], 1.0 op_sel_hi:[1,0]
	v_rcp_f32_e32 v14, v14
	v_rcp_f32_e32 v15, v15
	v_rcp_f32_e32 v12, v12
	v_rcp_f32_e32 v13, v13
	v_pk_mul_f32 v[0:1], v[0:1], v[18:19]
	s_nop 0
	v_pk_fma_f32 v[4:5], v[4:5], v[16:17], v[0:1]
	v_pk_mul_f32 v[0:1], v[2:3], v[14:15]
	v_cvt_pk_bf16_f32 v2, v4, v5
	v_lshlrev_b64 v[4:5], 12, v[24:25]
	v_pk_fma_f32 v[6:7], v[6:7], v[12:13], v[0:1]
	v_lshl_add_u64 v[4:5], s[8:9], 0, v[4:5]
	v_cvt_pk_bf16_f32 v0, v8, v9
	v_cvt_pk_bf16_f32 v1, v10, v11
	v_cvt_pk_bf16_f32 v3, v6, v7
	v_lshl_add_u64 v[4:5], v[4:5], 0, v[80:81]
	global_store_dwordx4 v[4:5], v[0:3], off
	s_cbranch_vccz .LBB0_1382
	s_waitcnt vmcnt(0)
	s_cmpk_gt_u32 s3, 0xff
	s_cbranch_scc1 .LBB0_1389
	s_barrier

; #define PG8_STAGE(bufoff, gbase, voff) do { _Pragma("unroll") for (int _i = 0; _i < 2; ++_i) \
;         __builtin_amdgcn_global_load_lds((const unsigned*)((const char*)(gbase) + (voff)[_i]), (LAS unsigned*)(lds + (bufoff) + ldsw + _i * 8192), 16, 0, 0); } while (0)
; #define PG8_LDA(dst, b, h) do { _Pragma("unroll") for (int m = 0; m < 4; ++m) _Pragma("unroll") for (int k = 0; k < 2; ++k) dst[m][k] = *(const LAS bf16x8*)(lds + PG8_SA(b, h) + aoff + m * 2048 + k * 1024); } while (0)
; #define PG8_WAIT_V(n) asm volatile("s_waitcnt vmcnt(" #n ")" ::: "memory")
; #define PG8_WAIT_L(n) asm volatile("s_waitcnt lgkmcnt(" #n ")" ::: "memory")
; template <class Epi, class Sched>
; __device__ __forceinline__ void gemm_phase(LAS unsigned char* lds, const Gemm g, const Sched& S, const Epi& E) {
;     ...
;         for (int t = 0; t < nt; t += 2) {
;             const bool last = (t == nt - 2);
;             const char* a1 = cA + (size_t)(t + 1) * kstep;
;             const char* a2 = last ? nA : cA + (size_t)(t + 2) * kstep; const char* b2 = last ? nB : cB + (size_t)(t + 2) * kstep;
;             const char* a3 = a2 + kstep; const char* b3 = b2 + kstep;
;             PG8_LDB(B0, 0, 0); PG8_SCHED; PG8_LDA(At, 0, 0); PG8_STAGE(PG8_SA(1, 1), a1 + hstepA, voffA);
;             PG8_WAIT_L(8); PG8_BAR; PG8_WAIT_L(0); PG8_MMA(0, 0, At, B0); PG8_BAR; PG8_SCHED;
;             PG8_LDB(B1, 0, 1); PG8_STAGE(PG8_SB(0, 0), b2, voffB);
;             PG8_BAR; PG8_WAIT_L(0); if constexpr (!Epi::DIAG) PG8_MMA(0, 1, At, B1); PG8_BAR;
;             PG8_LDA(At, 0, 1); PG8_STAGE(PG8_SA(0, 0), a2, voffA);
;             PG8_BAR; PG8_WAIT_L(0); if constexpr (!Epi::DIAG) PG8_MMA(1, 0, At, B0); PG8_BAR; PG8_SCHED;
;             PG8_STAGE(PG8_SB(0, 1), b2 + hstepB, voffB);
;             PG8_WAIT_V(6); PG8_BAR; PG8_MMA(1, 1, At, B1); PG8_BAR;
;             PG8_LDB(B0, 1, 0); PG8_SCHED; PG8_LDA(At, 1, 0); PG8_STAGE(PG8_SA(0, 1), a2 + hstepA, voffA);
;             PG8_WAIT_L(8); PG8_BAR; PG8_WAIT_L(0); PG8_MMA(0, 0, At, B0); PG8_BAR; PG8_SCHED;
;             PG8_LDB(B1, 1, 1); PG8_STAGE(PG8_SB(1, 0), b3, voffB);
;             PG8_BAR; PG8_WAIT_L(0); if constexpr (!Epi::DIAG) PG8_MMA(0, 1, At, B1); PG8_BAR;
;             PG8_LDA(At, 1, 1); PG8_STAGE(PG8_SA(1, 0), a3, voffA);
;             PG8_BAR; PG8_WAIT_L(0); if constexpr (!Epi::DIAG) PG8_MMA(1, 0, At, B0); PG8_BAR; PG8_SCHED;
.LBB0_1653:
	ds_read_b128 v[138:141], v155
	ds_read_b128 v[142:145], v155 offset:1024
	ds_read_b128 v[146:149], v155 offset:2048
	ds_read_b128 v[162:165], v155 offset:3072
	s_add_i32 s75, s34, 2
	s_add_u32 s35, s6, 0xfff80080
	s_addc_u32 s36, s7, -1
	s_cmp_eq_u32 s72, s34
	s_cselect_b32 s34, s71, s73
	s_cselect_b32 s37, s13, s36
	s_cselect_b32 s36, s15, s35
	s_cselect_b32 s35, s70, s74
	v_lshl_add_u64 v[150:151], s[6:7], 0, v[134:135]
	s_add_i32 m0, s43, 0xc000
	ds_read_b128 v[166:169], v156
	ds_read_b128 v[170:173], v156 offset:1024
	ds_read_b128 v[174:177], v156 offset:2048
	ds_read_b128 v[178:181], v156 offset:3072
	ds_read_b128 v[186:189], v156 offset:4096
	ds_read_b128 v[190:193], v156 offset:5120
	ds_read_b128 v[194:197], v156 offset:6144
	ds_read_b128 v[198:201], v156 offset:7168
	global_load_lds_dwordx4 v[150:151], off
	v_lshl_add_u64 v[150:151], s[6:7], 0, v[136:137]
	s_add_i32 m0, s43, 0xe000
	s_nop 0
	global_load_lds_dwordx4 v[150:151], off
	s_waitcnt lgkmcnt(8)
	s_barrier
	s_waitcnt lgkmcnt(0)
	s_setprio 1
	s_waitcnt lgkmcnt(0)
	v_mfma_f32_16x16x32_bf16 v[124:127], v[138:141], v[166:169], v[124:127]
	v_mfma_f32_16x16x32_bf16 v[120:123], v[146:149], v[166:169], v[120:123]
	v_mfma_f32_16x16x32_bf16 v[116:119], v[138:141], v[174:177], v[116:119]
	v_mfma_f32_16x16x32_bf16 v[112:115], v[146:149], v[174:177], v[112:115]
	v_mfma_f32_16x16x32_bf16 v[104:107], v[138:141], v[186:189], v[104:107]
	v_mfma_f32_16x16x32_bf16 v[96:99], v[146:149], v[186:189], v[96:99]
	v_mfma_f32_16x16x32_bf16 v[88:91], v[138:141], v[194:197], v[88:91]
	v_mfma_f32_16x16x32_bf16 v[80:83], v[146:149], v[194:197], v[80:83]
	v_mfma_f32_16x16x32_bf16 v[124:127], v[142:145], v[170:173], v[124:127]
	v_mfma_f32_16x16x32_bf16 v[120:123], v[162:165], v[170:173], v[120:123]
	v_mfma_f32_16x16x32_bf16 v[116:119], v[142:145], v[178:181], v[116:119]
	v_mfma_f32_16x16x32_bf16 v[112:115], v[162:165], v[178:181], v[112:115]
	v_mfma_f32_16x16x32_bf16 v[104:107], v[142:145], v[190:193], v[104:107]
	v_mfma_f32_16x16x32_bf16 v[96:99], v[162:165], v[190:193], v[96:99]
	v_mfma_f32_16x16x32_bf16 v[88:91], v[142:145], v[198:201], v[88:91]
	v_mfma_f32_16x16x32_bf16 v[80:83], v[162:165], v[198:201], v[80:83]
	s_setprio 0
	s_barrier
	s_add_i32 s76, s53, s42
	v_lshl_add_u64 v[150:151], s[34:35], 0, v[128:129]
	s_mov_b32 m0, s76
	ds_read_b128 v[202:205], v157
	ds_read_b128 v[206:209], v157 offset:1024
	ds_read_b128 v[210:213], v157 offset:2048
	ds_read_b128 v[214:217], v157 offset:3072
	global_load_lds_dwordx4 v[150:151], off
	v_lshl_add_u64 v[158:159], s[34:35], 0, v[130:131]
	s_add_i32 m0, s76, 0x2000
	s_nop 0
	global_load_lds_dwordx4 v[158:159], off
	s_barrier
	s_waitcnt lgkmcnt(0)
	s_setprio 1
	s_waitcnt lgkmcnt(0)
	v_mfma_f32_16x16x32_bf16 v[108:111], v[202:205], v[166:169], v[108:111]
	v_mfma_f32_16x16x32_bf16 v[100:103], v[210:213], v[166:169], v[100:103]
	v_mfma_f32_16x16x32_bf16 v[92:95], v[202:205], v[174:177], v[92:95]
	v_mfma_f32_16x16x32_bf16 v[84:87], v[210:213], v[174:177], v[84:87]
	v_mfma_f32_16x16x32_bf16 v[76:79], v[202:205], v[186:189], v[76:79]
	v_mfma_f32_16x16x32_bf16 v[72:75], v[210:213], v[186:189], v[72:75]
	v_mfma_f32_16x16x32_bf16 v[68:71], v[202:205], v[194:197], v[68:71]
	v_mfma_f32_16x16x32_bf16 v[64:67], v[210:213], v[194:197], v[64:67]
	v_mfma_f32_16x16x32_bf16 v[108:111], v[206:209], v[170:173], v[108:111]
	v_mfma_f32_16x16x32_bf16 v[100:103], v[214:217], v[170:173], v[100:103]
	v_mfma_f32_16x16x32_bf16 v[92:95], v[206:209], v[178:181], v[92:95]
	v_mfma_f32_16x16x32_bf16 v[84:87], v[214:217], v[178:181], v[84:87]
	v_mfma_f32_16x16x32_bf16 v[76:79], v[206:209], v[190:193], v[76:79]
	v_mfma_f32_16x16x32_bf16 v[72:75], v[214:217], v[190:193], v[72:75]
	v_mfma_f32_16x16x32_bf16 v[68:71], v[206:209], v[198:201], v[68:71]
	v_mfma_f32_16x16x32_bf16 v[64:67], v[214:217], v[198:201], v[64:67]
	s_setprio 0
	s_mov_b32 m0, s43
	v_lshl_add_u64 v[182:183], s[36:37], 0, v[128:129]
	s_barrier
	ds_read_b128 v[166:169], v156 offset:16384
	ds_read_b128 v[170:173], v156 offset:17408
	ds_read_b128 v[174:177], v156 offset:18432
	ds_read_b128 v[178:181], v156 offset:19456
	ds_read_b128 v[186:189], v156 offset:20480
	ds_read_b128 v[190:193], v156 offset:21504
	ds_read_b128 v[194:197], v156 offset:22528
	ds_read_b128 v[198:201], v156 offset:23552
	global_load_lds_dwordx4 v[182:183], off
	v_lshl_add_u64 v[218:219], s[36:37], 0, v[130:131]
	s_mov_b32 m0, s44
	s_nop 0
	global_load_lds_dwordx4 v[218:219], off
	s_barrier
	s_waitcnt lgkmcnt(0)
	s_setprio 1
	s_waitcnt lgkmcnt(0)
	v_mfma_f32_16x16x32_bf16 v[60:63], v[138:141], v[166:169], v[60:63]
	v_mfma_f32_16x16x32_bf16 v[56:59], v[146:149], v[166:169], v[56:59]
	v_mfma_f32_16x16x32_bf16 v[52:55], v[138:141], v[174:177], v[52:55]
	v_mfma_f32_16x16x32_bf16 v[48:51], v[146:149], v[174:177], v[48:51]
	v_mfma_f32_16x16x32_bf16 v[40:43], v[138:141], v[186:189], v[40:43]
	v_mfma_f32_16x16x32_bf16 v[32:35], v[146:149], v[186:189], v[32:35]
	v_mfma_f32_16x16x32_bf16 v[24:27], v[138:141], v[194:197], v[24:27]
	v_mfma_f32_16x16x32_bf16 v[16:19], v[146:149], v[194:197], v[16:19]
	v_mfma_f32_16x16x32_bf16 v[60:63], v[142:145], v[170:173], v[60:63]
	v_mfma_f32_16x16x32_bf16 v[56:59], v[162:165], v[170:173], v[56:59]
	v_mfma_f32_16x16x32_bf16 v[52:55], v[142:145], v[178:181], v[52:55]
	v_mfma_f32_16x16x32_bf16 v[48:51], v[162:165], v[178:181], v[48:51]
	v_mfma_f32_16x16x32_bf16 v[40:43], v[142:145], v[190:193], v[40:43]
	v_mfma_f32_16x16x32_bf16 v[32:35], v[162:165], v[190:193], v[32:35]
	v_mfma_f32_16x16x32_bf16 v[24:27], v[142:145], v[198:201], v[24:27]
	v_mfma_f32_16x16x32_bf16 v[16:19], v[162:165], v[198:201], v[16:19]
	s_setprio 0
	s_barrier
; #define PG8_STAGE(bufoff, gbase, voff) do { _Pragma("unroll") for (int _i = 0; _i < 2; ++_i) \
;         __builtin_amdgcn_global_load_lds((const unsigned*)((const char*)(gbase) + (voff)[_i]), (LAS unsigned*)(lds + (bufoff) + ldsw + _i * 8192), 16, 0, 0); } while (0)
; #define PG8_LDA(dst, b, h) do { _Pragma("unroll") for (int m = 0; m < 4; ++m) _Pragma("unroll") for (int k = 0; k < 2; ++k) dst[m][k] = *(const LAS bf16x8*)(lds + PG8_SA(b, h) + aoff + m * 2048 + k * 1024); } while (0)
; #define PG8_LDB(dst, b, h) do { _Pragma("unroll") for (int n = 0; n < 2; ++n) _Pragma("unroll") for (int k = 0; k < 2; ++k) dst[n][k] = *(const LAS bf16x8*)(lds + PG8_SB(b, h) + boff + n * 2048 + k * 1024); } while (0)
; #define PG8_WAIT_V(n) asm volatile("s_waitcnt vmcnt(" #n ")" ::: "memory")
; #define PG8_WAIT_L(n) asm volatile("s_waitcnt lgkmcnt(" #n ")" ::: "memory")
; template <class Epi, class Sched>
; __device__ __forceinline__ void gemm_phase(LAS unsigned char* lds, const Gemm g, const Sched& S, const Epi& E) {
;     ...
;             PG8_LDB(B0, 0, 0); PG8_SCHED; PG8_LDA(At, 0, 0); PG8_STAGE(PG8_SA(1, 1), a1 + hstepA, voffA);
;             PG8_WAIT_L(8); PG8_BAR; PG8_WAIT_L(0); PG8_MMA(0, 0, At, B0); PG8_BAR; PG8_SCHED;
;             PG8_LDB(B1, 0, 1); PG8_STAGE(PG8_SB(0, 0), b2, voffB);
;             PG8_BAR; PG8_WAIT_L(0); if constexpr (!Epi::DIAG) PG8_MMA(0, 1, At, B1); PG8_BAR;
;             PG8_LDA(At, 0, 1); PG8_STAGE(PG8_SA(0, 0), a2, voffA);
;             PG8_BAR; PG8_WAIT_L(0); if constexpr (!Epi::DIAG) PG8_MMA(1, 0, At, B0); PG8_BAR; PG8_SCHED;
;             PG8_STAGE(PG8_SB(0, 1), b2 + hstepB, voffB);
;             PG8_WAIT_V(6); PG8_BAR; PG8_MMA(1, 1, At, B1); PG8_BAR;
;             PG8_LDB(B0, 1, 0); PG8_SCHED; PG8_LDA(At, 1, 0); PG8_STAGE(PG8_SA(0, 1), a2 + hstepA, voffA);
;             PG8_WAIT_L(8); PG8_BAR; PG8_WAIT_L(0); PG8_MMA(0, 0, At, B0); PG8_BAR; PG8_SCHED;
;             PG8_LDB(B1, 1, 1); PG8_STAGE(PG8_SB(1, 0), b3, voffB);
;             PG8_BAR; PG8_WAIT_L(0); if constexpr (!Epi::DIAG) PG8_MMA(0, 1, At, B1); PG8_BAR;
;             PG8_LDA(At, 1, 1); PG8_STAGE(PG8_SA(1, 0), a3, voffA);
;             PG8_BAR; PG8_WAIT_L(0); if constexpr (!Epi::DIAG) PG8_MMA(1, 0, At, B0); PG8_BAR; PG8_SCHED;
;             PG8_STAGE(PG8_SB(1, 1), b3 + hstepB, voffB);
;             PG8_WAIT_V(6); PG8_BAR; PG8_MMA(1, 1, At, B1); PG8_BAR;
	s_add_u32 s76, s34, 0x80000
	s_addc_u32 s77, s35, 0
	s_add_i32 s78, s55, s42
	v_lshl_add_u64 v[138:139], s[76:77], 0, v[128:129]
	s_mov_b32 m0, s78
	s_nop 0
	global_load_lds_dwordx4 v[138:139], off
	v_lshl_add_u64 v[138:139], s[76:77], 0, v[130:131]
	s_add_i32 m0, s78, 0x2000
	s_nop 0
	global_load_lds_dwordx4 v[138:139], off
	s_waitcnt vmcnt(6)
	s_barrier
	s_setprio 1
	v_mfma_f32_16x16x32_bf16 v[44:47], v[202:205], v[166:169], v[44:47]
	v_mfma_f32_16x16x32_bf16 v[36:39], v[210:213], v[166:169], v[36:39]
	v_mfma_f32_16x16x32_bf16 v[28:31], v[202:205], v[174:177], v[28:31]
	v_mfma_f32_16x16x32_bf16 v[20:23], v[210:213], v[174:177], v[20:23]
	v_mfma_f32_16x16x32_bf16 v[12:15], v[202:205], v[186:189], v[12:15]
	v_mfma_f32_16x16x32_bf16 v[8:11], v[210:213], v[186:189], v[8:11]
	v_mfma_f32_16x16x32_bf16 v[4:7], v[202:205], v[194:197], v[4:7]
	v_mfma_f32_16x16x32_bf16 v[0:3], v[210:213], v[194:197], v[0:3]
	v_mfma_f32_16x16x32_bf16 v[44:47], v[206:209], v[170:173], v[44:47]
	v_mfma_f32_16x16x32_bf16 v[36:39], v[214:217], v[170:173], v[36:39]
	v_mfma_f32_16x16x32_bf16 v[28:31], v[206:209], v[178:181], v[28:31]
	v_mfma_f32_16x16x32_bf16 v[20:23], v[214:217], v[178:181], v[20:23]
	v_mfma_f32_16x16x32_bf16 v[12:15], v[206:209], v[190:193], v[12:15]
	v_mfma_f32_16x16x32_bf16 v[8:11], v[214:217], v[190:193], v[8:11]
	v_mfma_f32_16x16x32_bf16 v[4:7], v[206:209], v[198:201], v[4:7]
	v_mfma_f32_16x16x32_bf16 v[0:3], v[214:217], v[198:201], v[0:3]
	s_setprio 0
	s_add_i32 s76, 0, 0x18000
	v_add_u32_e32 v132, s76, v153
	s_barrier
	ds_read_b128 v[138:141], v132
	ds_read_b128 v[142:145], v132 offset:1024
	ds_read_b128 v[146:149], v132 offset:2048
	ds_read_b128 v[162:165], v132 offset:3072
	s_add_u32 s36, s36, 0x80000
	s_addc_u32 s37, s37, 0
	s_mov_b32 m0, s45
	v_lshl_add_u64 v[202:203], s[36:37], 0, v[128:129]
	ds_read_b128 v[166:169], v156 offset:32768
	ds_read_b128 v[170:173], v156 offset:33792
	ds_read_b128 v[174:177], v156 offset:34816
	ds_read_b128 v[178:181], v156 offset:35840
	ds_read_b128 v[186:189], v156 offset:36864
	ds_read_b128 v[190:193], v156 offset:37888
	ds_read_b128 v[194:197], v156 offset:38912
	ds_read_b128 v[198:201], v156 offset:39936
	global_load_lds_dwordx4 v[202:203], off
	v_lshl_add_u64 v[202:203], s[36:37], 0, v[130:131]
	s_mov_b32 m0, s46
	s_nop 0
	global_load_lds_dwordx4 v[202:203], off
	s_waitcnt lgkmcnt(8)
	s_barrier
	s_waitcnt lgkmcnt(0)
	s_setprio 1
	s_waitcnt lgkmcnt(0)
	v_mfma_f32_16x16x32_bf16 v[124:127], v[138:141], v[166:169], v[124:127]
	v_mfma_f32_16x16x32_bf16 v[120:123], v[146:149], v[166:169], v[120:123]
	v_mfma_f32_16x16x32_bf16 v[116:119], v[138:141], v[174:177], v[116:119]
	v_mfma_f32_16x16x32_bf16 v[112:115], v[146:149], v[174:177], v[112:115]
	v_mfma_f32_16x16x32_bf16 v[104:107], v[138:141], v[186:189], v[104:107]
	v_mfma_f32_16x16x32_bf16 v[96:99], v[146:149], v[186:189], v[96:99]
	v_mfma_f32_16x16x32_bf16 v[88:91], v[138:141], v[194:197], v[88:91]
	v_mfma_f32_16x16x32_bf16 v[80:83], v[146:149], v[194:197], v[80:83]
	v_mfma_f32_16x16x32_bf16 v[124:127], v[142:145], v[170:173], v[124:127]
	v_mfma_f32_16x16x32_bf16 v[120:123], v[162:165], v[170:173], v[120:123]
	v_mfma_f32_16x16x32_bf16 v[116:119], v[142:145], v[178:181], v[116:119]
	v_mfma_f32_16x16x32_bf16 v[112:115], v[162:165], v[178:181], v[112:115]
	v_mfma_f32_16x16x32_bf16 v[104:107], v[142:145], v[190:193], v[104:107]
	v_mfma_f32_16x16x32_bf16 v[96:99], v[162:165], v[190:193], v[96:99]
	v_mfma_f32_16x16x32_bf16 v[88:91], v[142:145], v[198:201], v[88:91]
	v_mfma_f32_16x16x32_bf16 v[80:83], v[162:165], v[198:201], v[80:83]
	s_setprio 0
	s_barrier
	s_add_i32 s36, 0, 0x1c000
	s_add_i32 s37, s76, s42
	v_add_u32_e32 v132, s36, v153
	v_lshl_add_u64 v[150:151], v[150:151], 0, s[24:25]
	s_mov_b32 m0, s37
	ds_read_b128 v[202:205], v132
	ds_read_b128 v[206:209], v132 offset:1024
	ds_read_b128 v[210:213], v132 offset:2048
	ds_read_b128 v[214:217], v132 offset:3072
	global_load_lds_dwordx4 v[150:151], off
	v_lshl_add_u64 v[150:151], v[158:159], 0, s[24:25]
	s_add_i32 m0, s37, 0x2000
	s_nop 0
	global_load_lds_dwordx4 v[150:151], off
	s_barrier
	s_waitcnt lgkmcnt(0)
	s_setprio 1
	s_waitcnt lgkmcnt(0)
	v_mfma_f32_16x16x32_bf16 v[108:111], v[202:205], v[166:169], v[108:111]
	v_mfma_f32_16x16x32_bf16 v[100:103], v[210:213], v[166:169], v[100:103]
	v_mfma_f32_16x16x32_bf16 v[92:95], v[202:205], v[174:177], v[92:95]
	v_mfma_f32_16x16x32_bf16 v[84:87], v[210:213], v[174:177], v[84:87]
	v_mfma_f32_16x16x32_bf16 v[76:79], v[202:205], v[186:189], v[76:79]
	v_mfma_f32_16x16x32_bf16 v[72:75], v[210:213], v[186:189], v[72:75]
	v_mfma_f32_16x16x32_bf16 v[68:71], v[202:205], v[194:197], v[68:71]
	v_mfma_f32_16x16x32_bf16 v[64:67], v[210:213], v[194:197], v[64:67]
	v_mfma_f32_16x16x32_bf16 v[108:111], v[206:209], v[170:173], v[108:111]
	v_mfma_f32_16x16x32_bf16 v[100:103], v[214:217], v[170:173], v[100:103]
	v_mfma_f32_16x16x32_bf16 v[92:95], v[206:209], v[178:181], v[92:95]
	v_mfma_f32_16x16x32_bf16 v[84:87], v[214:217], v[178:181], v[84:87]
	v_mfma_f32_16x16x32_bf16 v[76:79], v[206:209], v[190:193], v[76:79]
	v_mfma_f32_16x16x32_bf16 v[72:75], v[214:217], v[190:193], v[72:75]
	v_mfma_f32_16x16x32_bf16 v[68:71], v[206:209], v[198:201], v[68:71]
	v_mfma_f32_16x16x32_bf16 v[64:67], v[214:217], v[198:201], v[64:67]
	s_setprio 0
	s_mov_b32 m0, s50
	v_lshl_add_u64 v[150:151], v[182:183], 0, s[24:25]
	s_barrier
	ds_read_b128 v[166:169], v156 offset:49152
	ds_read_b128 v[170:173], v156 offset:50176
	ds_read_b128 v[174:177], v156 offset:51200
	ds_read_b128 v[178:181], v156 offset:52224
	ds_read_b128 v[186:189], v156 offset:53248
	ds_read_b128 v[190:193], v156 offset:54272
	ds_read_b128 v[194:197], v156 offset:55296
	ds_read_b128 v[198:201], v156 offset:56320
	global_load_lds_dwordx4 v[150:151], off
	v_lshl_add_u64 v[150:151], v[218:219], 0, s[24:25]
	s_mov_b32 m0, s51
	s_nop 0
	global_load_lds_dwordx4 v[150:151], off
	s_barrier
; #define PG8_STAGE(bufoff, gbase, voff) do { _Pragma("unroll") for (int _i = 0; _i < 2; ++_i) \
;         __builtin_amdgcn_global_load_lds((const unsigned*)((const char*)(gbase) + (voff)[_i]), (LAS unsigned*)(lds + (bufoff) + ldsw + _i * 8192), 16, 0, 0); } while (0)
; #define PG8_LDA(dst, b, h) do { _Pragma("unroll") for (int m = 0; m < 4; ++m) _Pragma("unroll") for (int k = 0; k < 2; ++k) dst[m][k] = *(const LAS bf16x8*)(lds + PG8_SA(b, h) + aoff + m * 2048 + k * 1024); } while (0)
; #define PG8_WAIT_V(n) asm volatile("s_waitcnt vmcnt(" #n ")" ::: "memory")
; template <class Epi, class Sched>
; __device__ __forceinline__ void gemm_phase(LAS unsigned char* lds, const Gemm g, const Sched& S, const Epi& E) {
;     ...
;             PG8_WAIT_V(6); PG8_BAR; PG8_MMA(1, 1, At, B1); PG8_BAR;
;             PG8_LDB(B0, 1, 0); PG8_SCHED; PG8_LDA(At, 1, 0); PG8_STAGE(PG8_SA(0, 1), a2 + hstepA, voffA);
;             PG8_WAIT_L(8); PG8_BAR; PG8_WAIT_L(0); PG8_MMA(0, 0, At, B0); PG8_BAR; PG8_SCHED;
;             PG8_LDB(B1, 1, 1); PG8_STAGE(PG8_SB(1, 0), b3, voffB);
;             PG8_BAR; PG8_WAIT_L(0); if constexpr (!Epi::DIAG) PG8_MMA(0, 1, At, B1); PG8_BAR;
;             PG8_LDA(At, 1, 1); PG8_STAGE(PG8_SA(1, 0), a3, voffA);
;             PG8_BAR; PG8_WAIT_L(0); if constexpr (!Epi::DIAG) PG8_MMA(1, 0, At, B0); PG8_BAR; PG8_SCHED;
;             PG8_STAGE(PG8_SB(1, 1), b3 + hstepB, voffB);
;             PG8_WAIT_V(6); PG8_BAR; PG8_MMA(1, 1, At, B1); PG8_BAR;
;         }
;         E(acc, cur, wr, wc, fr, fq);
;         if (!has_next) break;
;     __device__ __forceinline__ void operator()(const Acc& acc, const Unit& u, int wr, int wc, int fr, int fq) const {
;     ...
; #pragma unroll
;         for (int ai = 0; ai < 2; ++ai)
; #pragma unroll
;             for (int m = 0; m < 4; ++m) { const int row = row0 + ai * HALF + m * 16; const int b = bidx_of_row(row);
;                 const float* xr = (row < TP) ? x0p + (size_t)row * DM : x0s + (size_t)(row - TP) * DM; const float* gr = gate + (size_t)b * MODW; float* orow = X1 + (size_t)row * DM;
; #pragma unroll
;                 for (int bj = 0; bj < 2; ++bj)
; #pragma unroll
;                     for (int n = 0; n < 2; ++n) { const int c = col0 + bj * HALF + n * 16; const f32x4 xv = *(const f32x4*)(xr + c), gv = *(const f32x4*)(gr + c);
;                         *(f32x4*)(orow + c) = xv + gv * acc[ai][bj][m][n]; } }
	s_waitcnt lgkmcnt(0)
	s_setprio 1
	s_waitcnt lgkmcnt(0)
	v_mfma_f32_16x16x32_bf16 v[60:63], v[138:141], v[166:169], v[60:63]
	v_mfma_f32_16x16x32_bf16 v[56:59], v[146:149], v[166:169], v[56:59]
	v_mfma_f32_16x16x32_bf16 v[52:55], v[138:141], v[174:177], v[52:55]
	v_mfma_f32_16x16x32_bf16 v[48:51], v[146:149], v[174:177], v[48:51]
	v_mfma_f32_16x16x32_bf16 v[40:43], v[138:141], v[186:189], v[40:43]
	v_mfma_f32_16x16x32_bf16 v[32:35], v[146:149], v[186:189], v[32:35]
	v_mfma_f32_16x16x32_bf16 v[24:27], v[138:141], v[194:197], v[24:27]
	v_mfma_f32_16x16x32_bf16 v[16:19], v[146:149], v[194:197], v[16:19]
	v_mfma_f32_16x16x32_bf16 v[60:63], v[142:145], v[170:173], v[60:63]
	v_mfma_f32_16x16x32_bf16 v[56:59], v[162:165], v[170:173], v[56:59]
	v_mfma_f32_16x16x32_bf16 v[52:55], v[142:145], v[178:181], v[52:55]
	v_mfma_f32_16x16x32_bf16 v[48:51], v[162:165], v[178:181], v[48:51]
	v_mfma_f32_16x16x32_bf16 v[40:43], v[142:145], v[190:193], v[40:43]
	v_mfma_f32_16x16x32_bf16 v[32:35], v[162:165], v[190:193], v[32:35]
	v_mfma_f32_16x16x32_bf16 v[24:27], v[142:145], v[198:201], v[24:27]
	v_mfma_f32_16x16x32_bf16 v[16:19], v[162:165], v[198:201], v[16:19]
	s_setprio 0
	s_barrier
	s_add_u32 s34, s34, 0x80080
	s_addc_u32 s35, s35, 0
	s_add_i32 s36, s36, s42
	v_lshl_add_u64 v[138:139], s[34:35], 0, v[128:129]
	s_mov_b32 m0, s36
	s_nop 0
	global_load_lds_dwordx4 v[138:139], off
	v_lshl_add_u64 v[138:139], s[34:35], 0, v[130:131]
	s_add_i32 m0, s36, 0x2000
	s_nop 0
	global_load_lds_dwordx4 v[138:139], off
	s_waitcnt vmcnt(6)
	s_barrier
	s_setprio 1
	v_mfma_f32_16x16x32_bf16 v[44:47], v[202:205], v[166:169], v[44:47]
	v_mfma_f32_16x16x32_bf16 v[36:39], v[210:213], v[166:169], v[36:39]
	v_mfma_f32_16x16x32_bf16 v[28:31], v[202:205], v[174:177], v[28:31]
	v_mfma_f32_16x16x32_bf16 v[20:23], v[210:213], v[174:177], v[20:23]
	v_mfma_f32_16x16x32_bf16 v[12:15], v[202:205], v[186:189], v[12:15]
	v_mfma_f32_16x16x32_bf16 v[8:11], v[210:213], v[186:189], v[8:11]
	v_mfma_f32_16x16x32_bf16 v[4:7], v[202:205], v[194:197], v[4:7]
	v_mfma_f32_16x16x32_bf16 v[0:3], v[210:213], v[194:197], v[0:3]
	v_mfma_f32_16x16x32_bf16 v[44:47], v[206:209], v[170:173], v[44:47]
	v_mfma_f32_16x16x32_bf16 v[36:39], v[214:217], v[170:173], v[36:39]
	v_mfma_f32_16x16x32_bf16 v[28:31], v[206:209], v[178:181], v[28:31]
	v_mfma_f32_16x16x32_bf16 v[20:23], v[214:217], v[178:181], v[20:23]
	v_mfma_f32_16x16x32_bf16 v[12:15], v[206:209], v[190:193], v[12:15]
	v_mfma_f32_16x16x32_bf16 v[8:11], v[214:217], v[190:193], v[8:11]
	v_mfma_f32_16x16x32_bf16 v[4:7], v[206:209], v[198:201], v[4:7]
	v_mfma_f32_16x16x32_bf16 v[0:3], v[214:217], v[198:201], v[0:3]
	s_setprio 0
	s_add_u32 s6, s6, 0x100
	s_addc_u32 s7, s7, 0
	s_add_u32 s73, s73, 0x100
	s_addc_u32 s74, s74, 0
	s_cmp_ge_u32 s75, s67
	s_mov_b32 s34, s75
	s_barrier
	s_cbranch_scc0 .LBB0_1653
	s_lshl_b32 s13, s69, 8
	s_add_i32 s13, s13, s52
	v_or_b32_e32 v138, s13, v152
	v_lshl_or_b32 v142, s68, 8, v154
	s_cmp_gt_i32 s16, -1
	v_add_u32_e32 v140, 0xffffe000, v138
	s_mov_b64 s[6:7], -1
	s_cbranch_scc1 .LBB0_1688
	v_cmp_gt_i32_e32 vcc, s47, v138
	v_cmp_lt_i32_e64 s[6:7], s56, v138
	s_and_saveexec_b64 s[34:35], s[6:7]
	s_xor_b64 s[6:7], exec, s[34:35]
	v_mov_b32_e32 v141, v133
	v_lshlrev_b64 v[144:145], 13, v[140:141]
	v_mov_b32_e32 v139, v133
	v_lshl_add_u64 v[148:149], s[10:11], 0, v[144:145]
	v_lshlrev_b64 v[146:147], 13, v[138:139]
	s_andn2_saveexec_b64 s[6:7], s[6:7]
	v_ashrrev_i32_e32 v139, 31, v138
	v_lshlrev_b64 v[146:147], 13, v[138:139]
	v_lshl_add_u64 v[148:149], s[8:9], 0, v[146:147]
	s_or_b64 exec, exec, s[6:7]
	s_ashr_i32 s13, s13, 11
	v_lshrrev_b32_e32 v132, 2, v140
	v_or_b32_e32 v132, 4, v132
	v_mov_b32_e32 v139, s13
	v_cndmask_b32_e32 v132, v132, v139, vcc
	v_mov_b64_e32 v[144:145], s[22:23]
	v_ashrrev_i32_e32 v143, 31, v142
	v_mad_i64_i32 v[158:159], s[6:7], v132, s54, v[144:145]
	v_lshlrev_b64 v[144:145], 2, v[142:143]
	v_lshl_add_u64 v[166:167], v[148:149], 0, v[144:145]
	v_lshl_add_u64 v[158:159], v[158:159], 0, v[144:145]
	global_load_dwordx4 v[186:189], v[166:167], off
	global_load_dwordx4 v[202:205], v[158:159], off
	global_load_dwordx4 v[190:193], v[166:167], off offset:64
	global_load_dwordx4 v[206:209], v[158:159], off offset:64
	global_load_dwordx4 v[194:197], v[166:167], off offset:512
	global_load_dwordx4 v[210:213], v[158:159], off offset:512
	global_load_dwordx4 v[198:201], v[166:167], off offset:576
	global_load_dwordx4 v[214:217], v[158:159], off offset:576
	v_lshl_add_u64 v[146:147], s[26:27], 0, v[146:147]
	v_lshl_add_u64 v[168:169], v[146:147], 0, v[144:145]
	v_add_u32_e32 v132, 0xffffe010, v138
	s_waitcnt vmcnt(6)
	v_pk_fma_f32 v[188:189], v[126:127], v[204:205], v[188:189]
	v_pk_fma_f32 v[186:187], v[124:125], v[202:203], v[186:187]
	global_store_dwordx4 v[168:169], v[186:189], off
	v_or_b32_e32 v150, 16, v138
	v_cmp_gt_i32_e32 vcc, s47, v150
	v_cmp_lt_i32_e64 s[6:7], s56, v150
	s_waitcnt vmcnt(5)
	v_pk_fma_f32 v[192:193], v[122:123], v[208:209], v[192:193]
	v_pk_fma_f32 v[190:191], v[120:121], v[206:207], v[190:191]
	global_store_dwordx4 v[168:169], v[190:193], off offset:64
	s_waitcnt vmcnt(4)
	v_pk_fma_f32 v[196:197], v[110:111], v[212:213], v[196:197]
	v_pk_fma_f32 v[194:195], v[108:109], v[210:211], v[194:195]
	global_store_dwordx4 v[168:169], v[194:197], off offset:512
	s_waitcnt vmcnt(3)
;     __device__ __forceinline__ void operator()(const Acc& acc, const Unit& u, int wr, int wc, int fr, int fq) const {
;     ...
; #pragma unroll
;         for (int ai = 0; ai < 2; ++ai)
; #pragma unroll
;             for (int m = 0; m < 4; ++m) { const int row = row0 + ai * HALF + m * 16; const int b = bidx_of_row(row);
;                 const float* xr = (row < TP) ? x0p + (size_t)row * DM : x0s + (size_t)(row - TP) * DM; const float* gr = gate + (size_t)b * MODW; float* orow = X1 + (size_t)row * DM;
; #pragma unroll
;                 for (int bj = 0; bj < 2; ++bj)
; #pragma unroll
;                     for (int n = 0; n < 2; ++n) { const int c = col0 + bj * HALF + n * 16; const f32x4 xv = *(const f32x4*)(xr + c), gv = *(const f32x4*)(gr + c);
;                         *(f32x4*)(orow + c) = xv + gv * acc[ai][bj][m][n]; } }
	v_pk_fma_f32 v[200:201], v[102:103], v[216:217], v[200:201]
	v_pk_fma_f32 v[198:199], v[100:101], v[214:215], v[198:199]
	global_store_dwordx4 v[168:169], v[198:201], off offset:576
	s_and_saveexec_b64 s[34:35], s[6:7]
	s_xor_b64 s[6:7], exec, s[34:35]
	v_lshlrev_b64 v[146:147], 13, v[132:133]
	v_mov_b32_e32 v151, v133
	v_lshl_add_u64 v[148:149], s[10:11], 0, v[146:147]
	v_lshlrev_b64 v[146:147], 13, v[150:151]
	s_andn2_saveexec_b64 s[6:7], s[6:7]
	v_ashrrev_i32_e32 v151, 31, v150
	v_lshlrev_b64 v[146:147], 13, v[150:151]
	v_lshl_add_u64 v[148:149], s[8:9], 0, v[146:147]
	s_or_b64 exec, exec, s[6:7]
	v_lshrrev_b32_e32 v132, 2, v132
	v_add_u32_e32 v132, 4, v132
	v_mov_b32_e32 v139, s13
	v_cndmask_b32_e32 v132, v132, v139, vcc
	v_mov_b64_e32 v[150:151], s[22:23]
	v_mad_i64_i32 v[158:159], s[6:7], v132, s54, v[150:151]
	v_lshl_add_u64 v[166:167], v[148:149], 0, v[144:145]
	v_lshl_add_u64 v[158:159], v[158:159], 0, v[144:145]
	global_load_dwordx4 v[186:189], v[166:167], off
	global_load_dwordx4 v[202:205], v[158:159], off
	global_load_dwordx4 v[190:193], v[166:167], off offset:64
	global_load_dwordx4 v[206:209], v[158:159], off offset:64
	global_load_dwordx4 v[194:197], v[166:167], off offset:512
	global_load_dwordx4 v[210:213], v[158:159], off offset:512
	global_load_dwordx4 v[198:201], v[166:167], off offset:576
	global_load_dwordx4 v[214:217], v[158:159], off offset:576
	v_lshl_add_u64 v[146:147], s[26:27], 0, v[146:147]
	v_lshl_add_u64 v[168:169], v[146:147], 0, v[144:145]
	v_add_u32_e32 v132, 0xffffe020, v138
	s_waitcnt vmcnt(6)
	v_pk_fma_f32 v[188:189], v[118:119], v[204:205], v[188:189]
	v_pk_fma_f32 v[186:187], v[116:117], v[202:203], v[186:187]
	global_store_dwordx4 v[168:169], v[186:189], off
	v_or_b32_e32 v150, 32, v138
	v_cmp_gt_i32_e32 vcc, s47, v150
	v_cmp_lt_i32_e64 s[6:7], s56, v150
	s_waitcnt vmcnt(5)
	v_pk_fma_f32 v[192:193], v[114:115], v[208:209], v[192:193]
	v_pk_fma_f32 v[190:191], v[112:113], v[206:207], v[190:191]
	global_store_dwordx4 v[168:169], v[190:193], off offset:64
	s_waitcnt vmcnt(4)
	v_pk_fma_f32 v[196:197], v[94:95], v[212:213], v[196:197]
	v_pk_fma_f32 v[194:195], v[92:93], v[210:211], v[194:195]
	global_store_dwordx4 v[168:169], v[194:197], off offset:512
	s_waitcnt vmcnt(3)
	v_pk_fma_f32 v[200:201], v[86:87], v[216:217], v[200:201]
	v_pk_fma_f32 v[198:199], v[84:85], v[214:215], v[198:199]
	global_store_dwordx4 v[168:169], v[198:201], off offset:576
	s_and_saveexec_b64 s[34:35], s[6:7]
	s_xor_b64 s[6:7], exec, s[34:35]
	v_lshlrev_b64 v[146:147], 13, v[132:133]
	v_mov_b32_e32 v151, v133
	v_lshl_add_u64 v[148:149], s[10:11], 0, v[146:147]
	v_lshlrev_b64 v[146:147], 13, v[150:151]
	s_andn2_saveexec_b64 s[6:7], s[6:7]
	v_ashrrev_i32_e32 v151, 31, v150
	v_lshlrev_b64 v[146:147], 13, v[150:151]
	v_lshl_add_u64 v[148:149], s[8:9], 0, v[146:147]
	s_or_b64 exec, exec, s[6:7]
	v_lshrrev_b32_e32 v132, 2, v132
	v_or_b32_e32 v132, 4, v132
	v_mov_b32_e32 v139, s13
	v_cndmask_b32_e32 v132, v132, v139, vcc
	v_mov_b64_e32 v[150:151], s[22:23]
	v_mad_i64_i32 v[158:159], s[6:7], v132, s54, v[150:151]
	v_lshl_add_u64 v[166:167], v[148:149], 0, v[144:145]
	v_lshl_add_u64 v[158:159], v[158:159], 0, v[144:145]
	global_load_dwordx4 v[186:189], v[166:167], off
	global_load_dwordx4 v[202:205], v[158:159], off
	global_load_dwordx4 v[190:193], v[166:167], off offset:64
	global_load_dwordx4 v[206:209], v[158:159], off offset:64
	global_load_dwordx4 v[194:197], v[166:167], off offset:512
	global_load_dwordx4 v[210:213], v[158:159], off offset:512
	global_load_dwordx4 v[198:201], v[166:167], off offset:576
	global_load_dwordx4 v[214:217], v[158:159], off offset:576
	v_lshl_add_u64 v[146:147], s[26:27], 0, v[146:147]
	v_lshl_add_u64 v[168:169], v[146:147], 0, v[144:145]
	v_add_u32_e32 v132, 0xffffe030, v138
	s_waitcnt vmcnt(6)
	v_pk_fma_f32 v[188:189], v[106:107], v[204:205], v[188:189]
	v_pk_fma_f32 v[186:187], v[104:105], v[202:203], v[186:187]
	global_store_dwordx4 v[168:169], v[186:189], off
	v_or_b32_e32 v150, 48, v138
	v_cmp_gt_i32_e32 vcc, s47, v150
	v_cmp_lt_i32_e64 s[6:7], s56, v150
	s_waitcnt vmcnt(5)
	v_pk_fma_f32 v[192:193], v[98:99], v[208:209], v[192:193]
	v_pk_fma_f32 v[190:191], v[96:97], v[206:207], v[190:191]
	global_store_dwordx4 v[168:169], v[190:193], off offset:64
	s_waitcnt vmcnt(4)
	v_pk_fma_f32 v[196:197], v[78:79], v[212:213], v[196:197]
	v_pk_fma_f32 v[194:195], v[76:77], v[210:211], v[194:195]
	global_store_dwordx4 v[168:169], v[194:197], off offset:512
	s_waitcnt vmcnt(3)
	v_pk_fma_f32 v[200:201], v[74:75], v[216:217], v[200:201]
	v_pk_fma_f32 v[198:199], v[72:73], v[214:215], v[198:199]
	global_store_dwordx4 v[168:169], v[198:201], off offset:576
	s_and_saveexec_b64 s[34:35], s[6:7]
	s_xor_b64 s[6:7], exec, s[34:35]
	v_lshlrev_b64 v[146:147], 13, v[132:133]
	v_mov_b32_e32 v151, v133
	v_lshl_add_u64 v[148:149], s[10:11], 0, v[146:147]
	v_lshlrev_b64 v[146:147], 13, v[150:151]
	s_andn2_saveexec_b64 s[6:7], s[6:7]
	v_ashrrev_i32_e32 v151, 31, v150
	v_lshlrev_b64 v[146:147], 13, v[150:151]
	v_lshl_add_u64 v[148:149], s[8:9], 0, v[146:147]
	s_or_b64 exec, exec, s[6:7]
	v_lshrrev_b32_e32 v132, 2, v132
	v_add_u32_e32 v132, 4, v132
	v_mov_b32_e32 v139, s13
	v_cndmask_b32_e32 v132, v132, v139, vcc
	v_mov_b64_e32 v[150:151], s[22:23]
	v_mad_i64_i32 v[158:159], s[6:7], v132, s54, v[150:151]
	v_lshl_add_u64 v[166:167], v[148:149], 0, v[144:145]
	v_lshl_add_u64 v[158:159], v[158:159], 0, v[144:145]
	global_load_dwordx4 v[186:189], v[166:167], off
	global_load_dwordx4 v[202:205], v[158:159], off
	global_load_dwordx4 v[190:193], v[166:167], off offset:64
	global_load_dwordx4 v[206:209], v[158:159], off offset:64
	global_load_dwordx4 v[194:197], v[166:167], off offset:512
	global_load_dwordx4 v[210:213], v[158:159], off offset:512
	global_load_dwordx4 v[198:201], v[166:167], off offset:576
	global_load_dwordx4 v[214:217], v[158:159], off offset:576
	v_lshl_add_u64 v[146:147], s[26:27], 0, v[146:147]
	v_lshl_add_u64 v[168:169], v[146:147], 0, v[144:145]
	v_cmp_gt_i32_e32 vcc, s57, v138
	v_cmp_lt_i32_e64 s[6:7], s58, v138
	v_add_u32_e32 v132, 0xffffe080, v138
	s_waitcnt vmcnt(6)
;     __device__ __forceinline__ void operator()(const Acc& acc, const Unit& u, int wr, int wc, int fr, int fq) const {
;     ...
; #pragma unroll
;         for (int ai = 0; ai < 2; ++ai)
; #pragma unroll
;             for (int m = 0; m < 4; ++m) { const int row = row0 + ai * HALF + m * 16; const int b = bidx_of_row(row);
;                 const float* xr = (row < TP) ? x0p + (size_t)row * DM : x0s + (size_t)(row - TP) * DM; const float* gr = gate + (size_t)b * MODW; float* orow = X1 + (size_t)row * DM;
; #pragma unroll
;                 for (int bj = 0; bj < 2; ++bj)
; #pragma unroll
;                     for (int n = 0; n < 2; ++n) { const int c = col0 + bj * HALF + n * 16; const f32x4 xv = *(const f32x4*)(xr + c), gv = *(const f32x4*)(gr + c);
;                         *(f32x4*)(orow + c) = xv + gv * acc[ai][bj][m][n]; } }
	v_pk_fma_f32 v[188:189], v[90:91], v[204:205], v[188:189]
	v_pk_fma_f32 v[186:187], v[88:89], v[202:203], v[186:187]
	global_store_dwordx4 v[168:169], v[186:189], off
	s_waitcnt vmcnt(5)
	v_pk_fma_f32 v[192:193], v[82:83], v[208:209], v[192:193]
	v_pk_fma_f32 v[190:191], v[80:81], v[206:207], v[190:191]
	global_store_dwordx4 v[168:169], v[190:193], off offset:64
	s_waitcnt vmcnt(4)
	v_pk_fma_f32 v[196:197], v[70:71], v[212:213], v[196:197]
	v_pk_fma_f32 v[194:195], v[68:69], v[210:211], v[194:195]
	global_store_dwordx4 v[168:169], v[194:197], off offset:512
	v_add_u32_e32 v146, 0x80, v138
	s_waitcnt vmcnt(3)
	v_pk_fma_f32 v[200:201], v[66:67], v[216:217], v[200:201]
	v_pk_fma_f32 v[198:199], v[64:65], v[214:215], v[198:199]
	global_store_dwordx4 v[168:169], v[198:201], off offset:576
	s_and_saveexec_b64 s[34:35], s[6:7]
	s_xor_b64 s[6:7], exec, s[34:35]
	v_lshlrev_b64 v[148:149], 13, v[132:133]
	v_mov_b32_e32 v147, v133
	v_lshl_add_u64 v[150:151], s[10:11], 0, v[148:149]
	v_lshlrev_b64 v[148:149], 13, v[146:147]
	s_andn2_saveexec_b64 s[6:7], s[6:7]
	v_ashrrev_i32_e32 v147, 31, v146
	v_lshlrev_b64 v[148:149], 13, v[146:147]
	v_lshl_add_u64 v[150:151], s[8:9], 0, v[148:149]
	s_or_b64 exec, exec, s[6:7]
	v_lshrrev_b32_e32 v132, 2, v132
	v_ashrrev_i32_e32 v139, 11, v146
	v_or_b32_e32 v132, 4, v132
	v_cndmask_b32_e32 v132, v132, v139, vcc
	v_mov_b64_e32 v[146:147], s[22:23]
	v_mad_i64_i32 v[146:147], s[6:7], v132, s54, v[146:147]
	v_lshl_add_u64 v[150:151], v[150:151], 0, v[144:145]
	v_lshl_add_u64 v[158:159], v[146:147], 0, v[144:145]
	global_load_dwordx4 v[186:189], v[150:151], off
	global_load_dwordx4 v[202:205], v[158:159], off
	global_load_dwordx4 v[190:193], v[150:151], off offset:64
	global_load_dwordx4 v[206:209], v[158:159], off offset:64
	global_load_dwordx4 v[194:197], v[150:151], off offset:512
	global_load_dwordx4 v[210:213], v[158:159], off offset:512
	global_load_dwordx4 v[198:201], v[150:151], off offset:576
	global_load_dwordx4 v[214:217], v[158:159], off offset:576
	v_lshl_add_u64 v[146:147], s[26:27], 0, v[148:149]
	v_lshl_add_u64 v[170:171], v[146:147], 0, v[144:145]
	v_cmp_gt_i32_e32 vcc, s59, v138
	v_cmp_lt_i32_e64 s[6:7], s60, v138
	v_add_u32_e32 v132, 0xffffe090, v138
	s_waitcnt vmcnt(6)
	v_pk_fma_f32 v[148:149], v[62:63], v[204:205], v[188:189]
	v_pk_fma_f32 v[146:147], v[60:61], v[202:203], v[186:187]
	global_store_dwordx4 v[170:171], v[146:149], off
	s_waitcnt vmcnt(5)
	v_pk_fma_f32 v[192:193], v[58:59], v[208:209], v[192:193]
	v_pk_fma_f32 v[190:191], v[56:57], v[206:207], v[190:191]
	global_store_dwordx4 v[170:171], v[190:193], off offset:64
	s_waitcnt vmcnt(4)
	v_pk_fma_f32 v[196:197], v[46:47], v[212:213], v[196:197]
	v_pk_fma_f32 v[194:195], v[44:45], v[210:211], v[194:195]
	global_store_dwordx4 v[170:171], v[194:197], off offset:512
	v_add_u32_e32 v150, 0x90, v138
	s_waitcnt vmcnt(3)
	v_pk_fma_f32 v[200:201], v[38:39], v[216:217], v[200:201]
	v_pk_fma_f32 v[198:199], v[36:37], v[214:215], v[198:199]
	global_store_dwordx4 v[170:171], v[198:201], off offset:576
	s_and_saveexec_b64 s[34:35], s[6:7]
	s_xor_b64 s[6:7], exec, s[34:35]
	v_lshlrev_b64 v[146:147], 13, v[132:133]
	v_mov_b32_e32 v151, v133
	v_lshl_add_u64 v[148:149], s[10:11], 0, v[146:147]
	v_lshlrev_b64 v[146:147], 13, v[150:151]
	s_andn2_saveexec_b64 s[6:7], s[6:7]
	v_ashrrev_i32_e32 v151, 31, v150
	v_lshlrev_b64 v[146:147], 13, v[150:151]
	v_lshl_add_u64 v[148:149], s[8:9], 0, v[146:147]
	s_or_b64 exec, exec, s[6:7]
	v_lshrrev_b32_e32 v132, 2, v132
	v_add_u32_e32 v132, 4, v132
	v_cndmask_b32_e32 v132, v132, v139, vcc
	v_mov_b64_e32 v[150:151], s[22:23]
	v_mad_i64_i32 v[158:159], s[6:7], v132, s54, v[150:151]
	v_lshl_add_u64 v[166:167], v[148:149], 0, v[144:145]
	v_lshl_add_u64 v[158:159], v[158:159], 0, v[144:145]
	global_load_dwordx4 v[186:189], v[166:167], off
	global_load_dwordx4 v[202:205], v[158:159], off
	global_load_dwordx4 v[190:193], v[166:167], off offset:64
	global_load_dwordx4 v[206:209], v[158:159], off offset:64
	global_load_dwordx4 v[194:197], v[166:167], off offset:512
	global_load_dwordx4 v[210:213], v[158:159], off offset:512
	global_load_dwordx4 v[198:201], v[166:167], off offset:576
	global_load_dwordx4 v[214:217], v[158:159], off offset:576
	v_lshl_add_u64 v[146:147], s[26:27], 0, v[146:147]
	v_lshl_add_u64 v[168:169], v[146:147], 0, v[144:145]
	v_cmp_gt_i32_e32 vcc, s61, v138
	v_cmp_lt_i32_e64 s[6:7], s62, v138
	v_add_u32_e32 v132, 0xffffe0a0, v138
	s_waitcnt vmcnt(6)
	v_pk_fma_f32 v[188:189], v[54:55], v[204:205], v[188:189]
	v_pk_fma_f32 v[186:187], v[52:53], v[202:203], v[186:187]
	global_store_dwordx4 v[168:169], v[186:189], off
	v_add_u32_e32 v150, 0xa0, v138
	s_waitcnt vmcnt(5)
;     __device__ __forceinline__ void operator()(const Acc& acc, const Unit& u, int wr, int wc, int fr, int fq) const {
;     ...
; #pragma unroll
;         for (int ai = 0; ai < 2; ++ai)
; #pragma unroll
;             for (int m = 0; m < 4; ++m) { const int row = row0 + ai * HALF + m * 16; const int b = bidx_of_row(row);
;                 const float* xr = (row < TP) ? x0p + (size_t)row * DM : x0s + (size_t)(row - TP) * DM; const float* gr = gate + (size_t)b * MODW; float* orow = X1 + (size_t)row * DM;
; #pragma unroll
;                 for (int bj = 0; bj < 2; ++bj)
; #pragma unroll
;                     for (int n = 0; n < 2; ++n) { const int c = col0 + bj * HALF + n * 16; const f32x4 xv = *(const f32x4*)(xr + c), gv = *(const f32x4*)(gr + c);
;                         *(f32x4*)(orow + c) = xv + gv * acc[ai][bj][m][n]; } }
	v_pk_fma_f32 v[192:193], v[50:51], v[208:209], v[192:193]
	v_pk_fma_f32 v[190:191], v[48:49], v[206:207], v[190:191]
	global_store_dwordx4 v[168:169], v[190:193], off offset:64
	s_waitcnt vmcnt(4)
	v_pk_fma_f32 v[196:197], v[30:31], v[212:213], v[196:197]
	v_pk_fma_f32 v[194:195], v[28:29], v[210:211], v[194:195]
	global_store_dwordx4 v[168:169], v[194:197], off offset:512
	s_waitcnt vmcnt(3)
	v_pk_fma_f32 v[200:201], v[22:23], v[216:217], v[200:201]
	v_pk_fma_f32 v[198:199], v[20:21], v[214:215], v[198:199]
	global_store_dwordx4 v[168:169], v[198:201], off offset:576
	s_and_saveexec_b64 s[34:35], s[6:7]
	s_xor_b64 s[6:7], exec, s[34:35]
	v_lshlrev_b64 v[146:147], 13, v[132:133]
	v_mov_b32_e32 v151, v133
	v_lshl_add_u64 v[148:149], s[10:11], 0, v[146:147]
	v_lshlrev_b64 v[146:147], 13, v[150:151]
	s_andn2_saveexec_b64 s[6:7], s[6:7]
	v_ashrrev_i32_e32 v151, 31, v150
	v_lshlrev_b64 v[146:147], 13, v[150:151]
	v_lshl_add_u64 v[148:149], s[8:9], 0, v[146:147]
	s_or_b64 exec, exec, s[6:7]
	v_lshrrev_b32_e32 v132, 2, v132
	v_or_b32_e32 v132, 4, v132
	v_cndmask_b32_e32 v132, v132, v139, vcc
	v_mov_b64_e32 v[150:151], s[22:23]
	v_mad_i64_i32 v[158:159], s[6:7], v132, s54, v[150:151]
	v_lshl_add_u64 v[166:167], v[148:149], 0, v[144:145]
	v_lshl_add_u64 v[158:159], v[158:159], 0, v[144:145]
	global_load_dwordx4 v[186:189], v[166:167], off
	global_load_dwordx4 v[202:205], v[158:159], off
	global_load_dwordx4 v[190:193], v[166:167], off offset:64
	global_load_dwordx4 v[206:209], v[158:159], off offset:64
	global_load_dwordx4 v[194:197], v[166:167], off offset:512
	global_load_dwordx4 v[210:213], v[158:159], off offset:512
	global_load_dwordx4 v[198:201], v[166:167], off offset:576
	global_load_dwordx4 v[214:217], v[158:159], off offset:576
	v_lshl_add_u64 v[146:147], s[26:27], 0, v[146:147]
	v_lshl_add_u64 v[168:169], v[146:147], 0, v[144:145]
	v_cmp_gt_i32_e32 vcc, s63, v138
	v_cmp_lt_i32_e64 s[6:7], s64, v138
	v_add_u32_e32 v132, 0xffffe0b0, v138
	s_waitcnt vmcnt(6)
	v_pk_fma_f32 v[188:189], v[42:43], v[204:205], v[188:189]
	v_pk_fma_f32 v[186:187], v[40:41], v[202:203], v[186:187]
	global_store_dwordx4 v[168:169], v[186:189], off
	v_add_u32_e32 v150, 0xb0, v138
	s_waitcnt vmcnt(5)
	v_pk_fma_f32 v[192:193], v[34:35], v[208:209], v[192:193]
	v_pk_fma_f32 v[190:191], v[32:33], v[206:207], v[190:191]
	global_store_dwordx4 v[168:169], v[190:193], off offset:64
	s_waitcnt vmcnt(4)
	v_pk_fma_f32 v[196:197], v[14:15], v[212:213], v[196:197]
	v_pk_fma_f32 v[194:195], v[12:13], v[210:211], v[194:195]
	global_store_dwordx4 v[168:169], v[194:197], off offset:512
	s_waitcnt vmcnt(3)
	v_pk_fma_f32 v[200:201], v[10:11], v[216:217], v[200:201]
	v_pk_fma_f32 v[198:199], v[8:9], v[214:215], v[198:199]
	global_store_dwordx4 v[168:169], v[198:201], off offset:576
	s_and_saveexec_b64 s[34:35], s[6:7]
	s_xor_b64 s[6:7], exec, s[34:35]
	v_lshlrev_b64 v[146:147], 13, v[132:133]
	v_mov_b32_e32 v151, v133
	v_lshl_add_u64 v[148:149], s[10:11], 0, v[146:147]
	v_lshlrev_b64 v[146:147], 13, v[150:151]
	s_andn2_saveexec_b64 s[6:7], s[6:7]
	v_ashrrev_i32_e32 v151, 31, v150
	v_lshlrev_b64 v[146:147], 13, v[150:151]
	v_lshl_add_u64 v[148:149], s[8:9], 0, v[146:147]
	s_or_b64 exec, exec, s[6:7]
	v_lshrrev_b32_e32 v132, 2, v132
	v_add_u32_e32 v132, 4, v132
	v_cndmask_b32_e32 v132, v132, v139, vcc
	v_mov_b64_e32 v[150:151], s[22:23]
	v_mad_i64_i32 v[158:159], s[6:7], v132, s54, v[150:151]
	v_lshl_add_u64 v[166:167], v[148:149], 0, v[144:145]
	v_lshl_add_u64 v[158:159], v[158:159], 0, v[144:145]
	global_load_dwordx4 v[186:189], v[166:167], off
	global_load_dwordx4 v[202:205], v[158:159], off
	global_load_dwordx4 v[190:193], v[166:167], off offset:64
	global_load_dwordx4 v[206:209], v[158:159], off offset:64
	global_load_dwordx4 v[194:197], v[166:167], off offset:512
	global_load_dwordx4 v[210:213], v[158:159], off offset:512
	global_load_dwordx4 v[198:201], v[166:167], off offset:576
	global_load_dwordx4 v[214:217], v[158:159], off offset:576
	v_lshl_add_u64 v[146:147], s[26:27], 0, v[146:147]
	v_lshl_add_u64 v[168:169], v[146:147], 0, v[144:145]
	s_mov_b64 s[6:7], 0
	s_waitcnt vmcnt(6)
	v_pk_fma_f32 v[146:147], v[26:27], v[204:205], v[188:189]
	v_pk_fma_f32 v[144:145], v[24:25], v[202:203], v[186:187]
	global_store_dwordx4 v[168:169], v[144:147], off
	s_waitcnt vmcnt(5)
	v_pk_fma_f32 v[192:193], v[18:19], v[208:209], v[192:193]
	v_pk_fma_f32 v[190:191], v[16:17], v[206:207], v[190:191]
	global_store_dwordx4 v[168:169], v[190:193], off offset:64
	s_waitcnt vmcnt(4)
	v_pk_fma_f32 v[196:197], v[6:7], v[212:213], v[196:197]
	v_pk_fma_f32 v[194:195], v[4:5], v[210:211], v[194:195]
	global_store_dwordx4 v[168:169], v[194:197], off offset:512
	s_waitcnt vmcnt(3)
	v_pk_fma_f32 v[200:201], v[2:3], v[216:217], v[200:201]
	v_pk_fma_f32 v[198:199], v[0:1], v[214:215], v[198:199]
	global_store_dwordx4 v[168:169], v[198:201], off offset:576

; #define PG8_STAGE(bufoff, gbase, voff) do { _Pragma("unroll") for (int _i = 0; _i < 2; ++_i) \
;         __builtin_amdgcn_global_load_lds((const unsigned*)((const char*)(gbase) + (voff)[_i]), (LAS unsigned*)(lds + (bufoff) + ldsw + _i * 8192), 16, 0, 0); } while (0)
; #define PG8_LDA(dst, b, h) do { _Pragma("unroll") for (int m = 0; m < 4; ++m) _Pragma("unroll") for (int k = 0; k < 2; ++k) dst[m][k] = *(const LAS bf16x8*)(lds + PG8_SA(b, h) + aoff + m * 2048 + k * 1024); } while (0)
; #define PG8_LDB(dst, b, h) do { _Pragma("unroll") for (int n = 0; n < 2; ++n) _Pragma("unroll") for (int k = 0; k < 2; ++k) dst[n][k] = *(const LAS bf16x8*)(lds + PG8_SB(b, h) + boff + n * 2048 + k * 1024); } while (0)
; #define PG8_WAIT_V(n) asm volatile("s_waitcnt vmcnt(" #n ")" ::: "memory")
; #define PG8_WAIT_L(n) asm volatile("s_waitcnt lgkmcnt(" #n ")" ::: "memory")
; #define PG8_BAR __builtin_amdgcn_s_barrier()
; #define PG8_SCHED __builtin_amdgcn_sched_barrier(0)
; template <class Epi, class Sched>
; __device__ __forceinline__ void gemm_phase(LAS unsigned char* lds, const Gemm g, const Sched& S, const Epi& E) {
;     ...
;         for (int t = 0; t < nt; t += 2) {
;             const bool last = (t == nt - 2);
;             const char* a1 = cA + (size_t)(t + 1) * kstep;
;             const char* a2 = last ? nA : cA + (size_t)(t + 2) * kstep; const char* b2 = last ? nB : cB + (size_t)(t + 2) * kstep;
;             const char* a3 = a2 + kstep; const char* b3 = b2 + kstep;
;             PG8_LDB(B0, 0, 0); PG8_SCHED; PG8_LDA(At, 0, 0); PG8_STAGE(PG8_SA(1, 1), a1 + hstepA, voffA);
;             PG8_WAIT_L(8); PG8_BAR; PG8_WAIT_L(0); PG8_MMA(0, 0, At, B0); PG8_BAR; PG8_SCHED;
;             PG8_LDB(B1, 0, 1); PG8_STAGE(PG8_SB(0, 0), b2, voffB);
;             PG8_BAR; PG8_WAIT_L(0); if constexpr (!Epi::DIAG) PG8_MMA(0, 1, At, B1); PG8_BAR;
;             PG8_LDA(At, 0, 1); PG8_STAGE(PG8_SA(0, 0), a2, voffA);
;             PG8_BAR; PG8_WAIT_L(0); if constexpr (!Epi::DIAG) PG8_MMA(1, 0, At, B0); PG8_BAR; PG8_SCHED;
;             PG8_STAGE(PG8_SB(0, 1), b2 + hstepB, voffB);
;             PG8_WAIT_V(6); PG8_BAR; PG8_MMA(1, 1, At, B1); PG8_BAR;
;             PG8_LDB(B0, 1, 0); PG8_SCHED; PG8_LDA(At, 1, 0); PG8_STAGE(PG8_SA(0, 1), a2 + hstepA, voffA);
;             PG8_WAIT_L(8); PG8_BAR; PG8_WAIT_L(0); PG8_MMA(0, 0, At, B0); PG8_BAR; PG8_SCHED;
.LBB0_1915:
	ds_read_b128 v[138:141], v155
	ds_read_b128 v[142:145], v155 offset:1024
	ds_read_b128 v[146:149], v155 offset:2048
	ds_read_b128 v[162:165], v155 offset:3072
	s_add_i32 s68, s24, 2
	s_add_u32 s25, s6, 0xffea0080
	s_addc_u32 s26, s7, -1
	s_cmp_eq_u32 s28, s24
	s_cselect_b32 s24, s22, s29
	s_cselect_b32 s27, s21, s26
	s_cselect_b32 s26, s20, s25
	s_cselect_b32 s25, s23, s67
	v_lshl_add_u64 v[150:151], s[6:7], 0, v[134:135]
	s_add_i32 m0, s37, 0xc000
	ds_read_b128 v[166:169], v156
	ds_read_b128 v[170:173], v156 offset:1024
	ds_read_b128 v[174:177], v156 offset:2048
	ds_read_b128 v[178:181], v156 offset:3072
	ds_read_b128 v[186:189], v156 offset:4096
	ds_read_b128 v[190:193], v156 offset:5120
	ds_read_b128 v[194:197], v156 offset:6144
	ds_read_b128 v[198:201], v156 offset:7168
	global_load_lds_dwordx4 v[150:151], off
	v_lshl_add_u64 v[150:151], s[6:7], 0, v[136:137]
	s_add_i32 m0, s37, 0xe000
	s_nop 0
	global_load_lds_dwordx4 v[150:151], off
	s_waitcnt lgkmcnt(8)
	s_barrier
	s_waitcnt lgkmcnt(0)
	s_setprio 1
	s_waitcnt lgkmcnt(0)
	v_mfma_f32_16x16x32_bf16 v[124:127], v[138:141], v[166:169], v[124:127]
	v_mfma_f32_16x16x32_bf16 v[120:123], v[146:149], v[166:169], v[120:123]
	v_mfma_f32_16x16x32_bf16 v[116:119], v[138:141], v[174:177], v[116:119]
	v_mfma_f32_16x16x32_bf16 v[112:115], v[146:149], v[174:177], v[112:115]
	v_mfma_f32_16x16x32_bf16 v[104:107], v[138:141], v[186:189], v[104:107]
	v_mfma_f32_16x16x32_bf16 v[96:99], v[146:149], v[186:189], v[96:99]
	v_mfma_f32_16x16x32_bf16 v[88:91], v[138:141], v[194:197], v[88:91]
	v_mfma_f32_16x16x32_bf16 v[80:83], v[146:149], v[194:197], v[80:83]
	v_mfma_f32_16x16x32_bf16 v[124:127], v[142:145], v[170:173], v[124:127]
	v_mfma_f32_16x16x32_bf16 v[120:123], v[162:165], v[170:173], v[120:123]
	v_mfma_f32_16x16x32_bf16 v[116:119], v[142:145], v[178:181], v[116:119]
	v_mfma_f32_16x16x32_bf16 v[112:115], v[162:165], v[178:181], v[112:115]
	v_mfma_f32_16x16x32_bf16 v[104:107], v[142:145], v[190:193], v[104:107]
	v_mfma_f32_16x16x32_bf16 v[96:99], v[162:165], v[190:193], v[96:99]
	v_mfma_f32_16x16x32_bf16 v[88:91], v[142:145], v[198:201], v[88:91]
	v_mfma_f32_16x16x32_bf16 v[80:83], v[162:165], v[198:201], v[80:83]
	s_setprio 0
	s_barrier
	s_add_i32 s69, s47, s36
	v_lshl_add_u64 v[150:151], s[24:25], 0, v[128:129]
	s_mov_b32 m0, s69
	ds_read_b128 v[202:205], v157
	ds_read_b128 v[206:209], v157 offset:1024
	ds_read_b128 v[210:213], v157 offset:2048
	ds_read_b128 v[214:217], v157 offset:3072
	global_load_lds_dwordx4 v[150:151], off
	v_lshl_add_u64 v[158:159], s[24:25], 0, v[130:131]
	s_add_i32 m0, s69, 0x2000
	s_nop 0
	global_load_lds_dwordx4 v[158:159], off
	s_barrier
	s_waitcnt lgkmcnt(0)
	s_setprio 1
	s_waitcnt lgkmcnt(0)
	v_mfma_f32_16x16x32_bf16 v[108:111], v[202:205], v[166:169], v[108:111]
	v_mfma_f32_16x16x32_bf16 v[100:103], v[210:213], v[166:169], v[100:103]
	v_mfma_f32_16x16x32_bf16 v[92:95], v[202:205], v[174:177], v[92:95]
	v_mfma_f32_16x16x32_bf16 v[84:87], v[210:213], v[174:177], v[84:87]
	v_mfma_f32_16x16x32_bf16 v[76:79], v[202:205], v[186:189], v[76:79]
	v_mfma_f32_16x16x32_bf16 v[72:75], v[210:213], v[186:189], v[72:75]
	v_mfma_f32_16x16x32_bf16 v[68:71], v[202:205], v[194:197], v[68:71]
	v_mfma_f32_16x16x32_bf16 v[64:67], v[210:213], v[194:197], v[64:67]
	v_mfma_f32_16x16x32_bf16 v[108:111], v[206:209], v[170:173], v[108:111]
	v_mfma_f32_16x16x32_bf16 v[100:103], v[214:217], v[170:173], v[100:103]
	v_mfma_f32_16x16x32_bf16 v[92:95], v[206:209], v[178:181], v[92:95]
	v_mfma_f32_16x16x32_bf16 v[84:87], v[214:217], v[178:181], v[84:87]
	v_mfma_f32_16x16x32_bf16 v[76:79], v[206:209], v[190:193], v[76:79]
	v_mfma_f32_16x16x32_bf16 v[72:75], v[214:217], v[190:193], v[72:75]
	v_mfma_f32_16x16x32_bf16 v[68:71], v[206:209], v[198:201], v[68:71]
	v_mfma_f32_16x16x32_bf16 v[64:67], v[214:217], v[198:201], v[64:67]
	s_setprio 0
	s_mov_b32 m0, s37
	v_lshl_add_u64 v[182:183], s[26:27], 0, v[128:129]
	s_barrier
	ds_read_b128 v[166:169], v156 offset:16384
	ds_read_b128 v[170:173], v156 offset:17408
	ds_read_b128 v[174:177], v156 offset:18432
	ds_read_b128 v[178:181], v156 offset:19456
	ds_read_b128 v[186:189], v156 offset:20480
	ds_read_b128 v[190:193], v156 offset:21504
	ds_read_b128 v[194:197], v156 offset:22528
	ds_read_b128 v[198:201], v156 offset:23552
	global_load_lds_dwordx4 v[182:183], off
	v_lshl_add_u64 v[218:219], s[26:27], 0, v[130:131]
	s_mov_b32 m0, s38
	s_nop 0
	global_load_lds_dwordx4 v[218:219], off
	s_barrier
	s_waitcnt lgkmcnt(0)
	s_setprio 1
	s_waitcnt lgkmcnt(0)
	v_mfma_f32_16x16x32_bf16 v[60:63], v[138:141], v[166:169], v[60:63]
	v_mfma_f32_16x16x32_bf16 v[56:59], v[146:149], v[166:169], v[56:59]
	v_mfma_f32_16x16x32_bf16 v[52:55], v[138:141], v[174:177], v[52:55]
	v_mfma_f32_16x16x32_bf16 v[48:51], v[146:149], v[174:177], v[48:51]
	v_mfma_f32_16x16x32_bf16 v[40:43], v[138:141], v[186:189], v[40:43]
	v_mfma_f32_16x16x32_bf16 v[32:35], v[146:149], v[186:189], v[32:35]
	v_mfma_f32_16x16x32_bf16 v[24:27], v[138:141], v[194:197], v[24:27]
	v_mfma_f32_16x16x32_bf16 v[16:19], v[146:149], v[194:197], v[16:19]
	v_mfma_f32_16x16x32_bf16 v[60:63], v[142:145], v[170:173], v[60:63]
	v_mfma_f32_16x16x32_bf16 v[56:59], v[162:165], v[170:173], v[56:59]
	v_mfma_f32_16x16x32_bf16 v[52:55], v[142:145], v[178:181], v[52:55]
	v_mfma_f32_16x16x32_bf16 v[48:51], v[162:165], v[178:181], v[48:51]
	v_mfma_f32_16x16x32_bf16 v[40:43], v[142:145], v[190:193], v[40:43]
	v_mfma_f32_16x16x32_bf16 v[32:35], v[162:165], v[190:193], v[32:35]
	v_mfma_f32_16x16x32_bf16 v[24:27], v[142:145], v[198:201], v[24:27]
	v_mfma_f32_16x16x32_bf16 v[16:19], v[162:165], v[198:201], v[16:19]
	s_setprio 0
	s_barrier
; #define PG8_STAGE(bufoff, gbase, voff) do { _Pragma("unroll") for (int _i = 0; _i < 2; ++_i) \
;         __builtin_amdgcn_global_load_lds((const unsigned*)((const char*)(gbase) + (voff)[_i]), (LAS unsigned*)(lds + (bufoff) + ldsw + _i * 8192), 16, 0, 0); } while (0)
; #define PG8_LDA(dst, b, h) do { _Pragma("unroll") for (int m = 0; m < 4; ++m) _Pragma("unroll") for (int k = 0; k < 2; ++k) dst[m][k] = *(const LAS bf16x8*)(lds + PG8_SA(b, h) + aoff + m * 2048 + k * 1024); } while (0)
; #define PG8_LDB(dst, b, h) do { _Pragma("unroll") for (int n = 0; n < 2; ++n) _Pragma("unroll") for (int k = 0; k < 2; ++k) dst[n][k] = *(const LAS bf16x8*)(lds + PG8_SB(b, h) + boff + n * 2048 + k * 1024); } while (0)
; #define PG8_MMA(ai, bj, At, Bt) do { __builtin_amdgcn_s_setprio(1); _Pragma("unroll") for (int m = 0; m < 4; ++m) _Pragma("unroll") for (int n = 0; n < 2; ++n) _Pragma("unroll") for (int k = 0; k < 2; ++k) \
;         acc[ai][bj][m][n] = __builtin_amdgcn_mfma_f32_16x16x32_bf16(Bt[n][k], At[m][k], acc[ai][bj][m][n], 0, 0, 0); __builtin_amdgcn_s_setprio(0); } while (0)
; #define PG8_WAIT_V(n) asm volatile("s_waitcnt vmcnt(" #n ")" ::: "memory")
; #define PG8_WAIT_L(n) asm volatile("s_waitcnt lgkmcnt(" #n ")" ::: "memory")
; #define PG8_BAR __builtin_amdgcn_s_barrier()
; #define PG8_SCHED __builtin_amdgcn_sched_barrier(0)
; template <class Epi, class Sched>
; __device__ __forceinline__ void gemm_phase(LAS unsigned char* lds, const Gemm g, const Sched& S, const Epi& E) {
;     ...
;             PG8_WAIT_V(6); PG8_BAR; PG8_MMA(1, 1, At, B1); PG8_BAR;
;             PG8_LDB(B0, 1, 0); PG8_SCHED; PG8_LDA(At, 1, 0); PG8_STAGE(PG8_SA(0, 1), a2 + hstepA, voffA);
;             PG8_WAIT_L(8); PG8_BAR; PG8_WAIT_L(0); PG8_MMA(0, 0, At, B0); PG8_BAR; PG8_SCHED;
;             PG8_LDB(B1, 1, 1); PG8_STAGE(PG8_SB(1, 0), b3, voffB);
;             PG8_BAR; PG8_WAIT_L(0); if constexpr (!Epi::DIAG) PG8_MMA(0, 1, At, B1); PG8_BAR;
;             PG8_LDA(At, 1, 1); PG8_STAGE(PG8_SA(1, 0), a3, voffA);
;             PG8_BAR; PG8_WAIT_L(0); if constexpr (!Epi::DIAG) PG8_MMA(1, 0, At, B0); PG8_BAR; PG8_SCHED;
;             PG8_STAGE(PG8_SB(1, 1), b3 + hstepB, voffB);
;             PG8_WAIT_V(6); PG8_BAR; PG8_MMA(1, 1, At, B1); PG8_BAR;
	s_add_u32 s70, s24, 0x160000
	s_addc_u32 s71, s25, 0
	s_add_i32 s69, s49, s36
	v_lshl_add_u64 v[138:139], s[70:71], 0, v[128:129]
	s_mov_b32 m0, s69
	s_nop 0
	global_load_lds_dwordx4 v[138:139], off
	v_lshl_add_u64 v[138:139], s[70:71], 0, v[130:131]
	s_add_i32 m0, s69, 0x2000
	s_nop 0
	global_load_lds_dwordx4 v[138:139], off
	s_waitcnt vmcnt(6)
	s_barrier
	s_setprio 1
	v_mfma_f32_16x16x32_bf16 v[44:47], v[202:205], v[166:169], v[44:47]
	v_mfma_f32_16x16x32_bf16 v[36:39], v[210:213], v[166:169], v[36:39]
	v_mfma_f32_16x16x32_bf16 v[28:31], v[202:205], v[174:177], v[28:31]
	v_mfma_f32_16x16x32_bf16 v[20:23], v[210:213], v[174:177], v[20:23]
	v_mfma_f32_16x16x32_bf16 v[12:15], v[202:205], v[186:189], v[12:15]
	v_mfma_f32_16x16x32_bf16 v[8:11], v[210:213], v[186:189], v[8:11]
	v_mfma_f32_16x16x32_bf16 v[4:7], v[202:205], v[194:197], v[4:7]
	v_mfma_f32_16x16x32_bf16 v[0:3], v[210:213], v[194:197], v[0:3]
	v_mfma_f32_16x16x32_bf16 v[44:47], v[206:209], v[170:173], v[44:47]
	v_mfma_f32_16x16x32_bf16 v[36:39], v[214:217], v[170:173], v[36:39]
	v_mfma_f32_16x16x32_bf16 v[28:31], v[206:209], v[178:181], v[28:31]
	v_mfma_f32_16x16x32_bf16 v[20:23], v[214:217], v[178:181], v[20:23]
	v_mfma_f32_16x16x32_bf16 v[12:15], v[206:209], v[190:193], v[12:15]
	v_mfma_f32_16x16x32_bf16 v[8:11], v[214:217], v[190:193], v[8:11]
	v_mfma_f32_16x16x32_bf16 v[4:7], v[206:209], v[198:201], v[4:7]
	v_mfma_f32_16x16x32_bf16 v[0:3], v[214:217], v[198:201], v[0:3]
	s_setprio 0
	s_add_i32 s69, 0, 0x18000
	v_add_u32_e32 v132, s69, v153
	s_barrier
	ds_read_b128 v[138:141], v132
	ds_read_b128 v[142:145], v132 offset:1024
	ds_read_b128 v[146:149], v132 offset:2048
	ds_read_b128 v[162:165], v132 offset:3072
	s_add_u32 s26, s26, 0x160000
	s_addc_u32 s27, s27, 0
	s_mov_b32 m0, s39
	v_lshl_add_u64 v[202:203], s[26:27], 0, v[128:129]
	ds_read_b128 v[166:169], v156 offset:32768
	ds_read_b128 v[170:173], v156 offset:33792
	ds_read_b128 v[174:177], v156 offset:34816
	ds_read_b128 v[178:181], v156 offset:35840
	ds_read_b128 v[186:189], v156 offset:36864
	ds_read_b128 v[190:193], v156 offset:37888
	ds_read_b128 v[194:197], v156 offset:38912
	ds_read_b128 v[198:201], v156 offset:39936
	global_load_lds_dwordx4 v[202:203], off
	v_lshl_add_u64 v[202:203], s[26:27], 0, v[130:131]
	s_mov_b32 m0, s40
	s_nop 0
	global_load_lds_dwordx4 v[202:203], off
	s_waitcnt lgkmcnt(8)
	s_barrier
	s_waitcnt lgkmcnt(0)
	s_setprio 1
	s_waitcnt lgkmcnt(0)
	v_mfma_f32_16x16x32_bf16 v[124:127], v[138:141], v[166:169], v[124:127]
	v_mfma_f32_16x16x32_bf16 v[120:123], v[146:149], v[166:169], v[120:123]
	v_mfma_f32_16x16x32_bf16 v[116:119], v[138:141], v[174:177], v[116:119]
	v_mfma_f32_16x16x32_bf16 v[112:115], v[146:149], v[174:177], v[112:115]
	v_mfma_f32_16x16x32_bf16 v[104:107], v[138:141], v[186:189], v[104:107]
	v_mfma_f32_16x16x32_bf16 v[96:99], v[146:149], v[186:189], v[96:99]
	v_mfma_f32_16x16x32_bf16 v[88:91], v[138:141], v[194:197], v[88:91]
	v_mfma_f32_16x16x32_bf16 v[80:83], v[146:149], v[194:197], v[80:83]
	v_mfma_f32_16x16x32_bf16 v[124:127], v[142:145], v[170:173], v[124:127]
	v_mfma_f32_16x16x32_bf16 v[120:123], v[162:165], v[170:173], v[120:123]
	v_mfma_f32_16x16x32_bf16 v[116:119], v[142:145], v[178:181], v[116:119]
	v_mfma_f32_16x16x32_bf16 v[112:115], v[162:165], v[178:181], v[112:115]
	v_mfma_f32_16x16x32_bf16 v[104:107], v[142:145], v[190:193], v[104:107]
	v_mfma_f32_16x16x32_bf16 v[96:99], v[162:165], v[190:193], v[96:99]
	v_mfma_f32_16x16x32_bf16 v[88:91], v[142:145], v[198:201], v[88:91]
	v_mfma_f32_16x16x32_bf16 v[80:83], v[162:165], v[198:201], v[80:83]
	s_setprio 0
	s_barrier
	s_add_i32 s26, 0, 0x1c000
	s_add_i32 s27, s69, s36
	v_add_u32_e32 v132, s26, v153
	v_lshl_add_u64 v[150:151], v[150:151], 0, s[16:17]
	s_mov_b32 m0, s27
	ds_read_b128 v[202:205], v132
	ds_read_b128 v[206:209], v132 offset:1024
	ds_read_b128 v[210:213], v132 offset:2048
	ds_read_b128 v[214:217], v132 offset:3072
	global_load_lds_dwordx4 v[150:151], off
	v_lshl_add_u64 v[150:151], v[158:159], 0, s[16:17]
	s_add_i32 m0, s27, 0x2000
	s_nop 0
	global_load_lds_dwordx4 v[150:151], off
	s_barrier
	s_waitcnt lgkmcnt(0)
	s_setprio 1
	s_waitcnt lgkmcnt(0)
	v_mfma_f32_16x16x32_bf16 v[108:111], v[202:205], v[166:169], v[108:111]
	v_mfma_f32_16x16x32_bf16 v[100:103], v[210:213], v[166:169], v[100:103]
	v_mfma_f32_16x16x32_bf16 v[92:95], v[202:205], v[174:177], v[92:95]
	v_mfma_f32_16x16x32_bf16 v[84:87], v[210:213], v[174:177], v[84:87]
	v_mfma_f32_16x16x32_bf16 v[76:79], v[202:205], v[186:189], v[76:79]
	v_mfma_f32_16x16x32_bf16 v[72:75], v[210:213], v[186:189], v[72:75]
	v_mfma_f32_16x16x32_bf16 v[68:71], v[202:205], v[194:197], v[68:71]
	v_mfma_f32_16x16x32_bf16 v[64:67], v[210:213], v[194:197], v[64:67]
	v_mfma_f32_16x16x32_bf16 v[108:111], v[206:209], v[170:173], v[108:111]
	v_mfma_f32_16x16x32_bf16 v[100:103], v[214:217], v[170:173], v[100:103]
	v_mfma_f32_16x16x32_bf16 v[92:95], v[206:209], v[178:181], v[92:95]
	v_mfma_f32_16x16x32_bf16 v[84:87], v[214:217], v[178:181], v[84:87]
	v_mfma_f32_16x16x32_bf16 v[76:79], v[206:209], v[190:193], v[76:79]
	v_mfma_f32_16x16x32_bf16 v[72:75], v[214:217], v[190:193], v[72:75]
	v_mfma_f32_16x16x32_bf16 v[68:71], v[206:209], v[198:201], v[68:71]
	v_mfma_f32_16x16x32_bf16 v[64:67], v[214:217], v[198:201], v[64:67]
	s_setprio 0
	s_mov_b32 m0, s45
	v_lshl_add_u64 v[150:151], v[182:183], 0, s[16:17]
	s_barrier
	ds_read_b128 v[166:169], v156 offset:49152
	ds_read_b128 v[170:173], v156 offset:50176
	ds_read_b128 v[174:177], v156 offset:51200
	ds_read_b128 v[178:181], v156 offset:52224
	ds_read_b128 v[186:189], v156 offset:53248
	ds_read_b128 v[190:193], v156 offset:54272
	ds_read_b128 v[194:197], v156 offset:55296
	ds_read_b128 v[198:201], v156 offset:56320
	global_load_lds_dwordx4 v[150:151], off
	v_lshl_add_u64 v[150:151], v[218:219], 0, s[16:17]
	s_mov_b32 m0, s46
	s_nop 0
	global_load_lds_dwordx4 v[150:151], off
	s_barrier
; #define PG8_STAGE(bufoff, gbase, voff) do { _Pragma("unroll") for (int _i = 0; _i < 2; ++_i) \
;         __builtin_amdgcn_global_load_lds((const unsigned*)((const char*)(gbase) + (voff)[_i]), (LAS unsigned*)(lds + (bufoff) + ldsw + _i * 8192), 16, 0, 0); } while (0)
; #define PG8_MMA(ai, bj, At, Bt) do { __builtin_amdgcn_s_setprio(1); _Pragma("unroll") for (int m = 0; m < 4; ++m) _Pragma("unroll") for (int n = 0; n < 2; ++n) _Pragma("unroll") for (int k = 0; k < 2; ++k) \
;         acc[ai][bj][m][n] = __builtin_amdgcn_mfma_f32_16x16x32_bf16(Bt[n][k], At[m][k], acc[ai][bj][m][n], 0, 0, 0); __builtin_amdgcn_s_setprio(0); } while (0)
; #define PG8_WAIT_V(n) asm volatile("s_waitcnt vmcnt(" #n ")" ::: "memory")
; #define PG8_WAIT_L(n) asm volatile("s_waitcnt lgkmcnt(" #n ")" ::: "memory")
; #define PG8_BAR __builtin_amdgcn_s_barrier()
; #define PG8_SCHED __builtin_amdgcn_sched_barrier(0)
; template <class Epi, class Sched>
; __device__ __forceinline__ void gemm_phase(LAS unsigned char* lds, const Gemm g, const Sched& S, const Epi& E) {
;     ...
;             PG8_BAR; PG8_WAIT_L(0); if constexpr (!Epi::DIAG) PG8_MMA(1, 0, At, B0); PG8_BAR; PG8_SCHED;
;             PG8_STAGE(PG8_SB(1, 1), b3 + hstepB, voffB);
;             PG8_WAIT_V(6); PG8_BAR; PG8_MMA(1, 1, At, B1); PG8_BAR;
;     __device__ __forceinline__ void operator()(const Acc& acc, const Unit& u, int wr, int wc, int fr, int fq) const {
;     ...
; #pragma unroll
;         for (int ai = 0; ai < 2; ++ai)
; #pragma unroll
;             for (int m = 0; m < 4; ++m) { const int row = row0 + ai * HALF + m * 16; const int b = bidx_of_row(row);
;                 const float* xr = (row < TP) ? x0p + (size_t)row * DM : x0s + (size_t)(row - TP) * DM; const float* gr = gate + (size_t)b * MODW; float* orow = X1 + (size_t)row * DM;
; #pragma unroll
;                 for (int bj = 0; bj < 2; ++bj)
; #pragma unroll
;                     for (int n = 0; n < 2; ++n) { const int c = col0 + bj * HALF + n * 16; const f32x4 xv = *(const f32x4*)(xr + c), gv = *(const f32x4*)(gr + c);
;                         *(f32x4*)(orow + c) = xv + gv * acc[ai][bj][m][n]; } }
	s_waitcnt lgkmcnt(0)
	s_setprio 1
	s_waitcnt lgkmcnt(0)
	v_mfma_f32_16x16x32_bf16 v[60:63], v[138:141], v[166:169], v[60:63]
	v_mfma_f32_16x16x32_bf16 v[56:59], v[146:149], v[166:169], v[56:59]
	v_mfma_f32_16x16x32_bf16 v[52:55], v[138:141], v[174:177], v[52:55]
	v_mfma_f32_16x16x32_bf16 v[48:51], v[146:149], v[174:177], v[48:51]
	v_mfma_f32_16x16x32_bf16 v[40:43], v[138:141], v[186:189], v[40:43]
	v_mfma_f32_16x16x32_bf16 v[32:35], v[146:149], v[186:189], v[32:35]
	v_mfma_f32_16x16x32_bf16 v[24:27], v[138:141], v[194:197], v[24:27]
	v_mfma_f32_16x16x32_bf16 v[16:19], v[146:149], v[194:197], v[16:19]
	v_mfma_f32_16x16x32_bf16 v[60:63], v[142:145], v[170:173], v[60:63]
	v_mfma_f32_16x16x32_bf16 v[56:59], v[162:165], v[170:173], v[56:59]
	v_mfma_f32_16x16x32_bf16 v[52:55], v[142:145], v[178:181], v[52:55]
	v_mfma_f32_16x16x32_bf16 v[48:51], v[162:165], v[178:181], v[48:51]
	v_mfma_f32_16x16x32_bf16 v[40:43], v[142:145], v[190:193], v[40:43]
	v_mfma_f32_16x16x32_bf16 v[32:35], v[162:165], v[190:193], v[32:35]
	v_mfma_f32_16x16x32_bf16 v[24:27], v[142:145], v[198:201], v[24:27]
	v_mfma_f32_16x16x32_bf16 v[16:19], v[162:165], v[198:201], v[16:19]
	s_setprio 0
	s_barrier
	s_add_u32 s24, s24, 0x160080
	s_addc_u32 s25, s25, 0
	s_add_i32 s26, s26, s36
	v_lshl_add_u64 v[138:139], s[24:25], 0, v[128:129]
	s_mov_b32 m0, s26
	s_nop 0
	global_load_lds_dwordx4 v[138:139], off
	v_lshl_add_u64 v[138:139], s[24:25], 0, v[130:131]
	s_add_i32 m0, s26, 0x2000
	s_nop 0
	global_load_lds_dwordx4 v[138:139], off
	s_waitcnt vmcnt(6)
	s_barrier
	s_setprio 1
	v_mfma_f32_16x16x32_bf16 v[44:47], v[202:205], v[166:169], v[44:47]
	v_mfma_f32_16x16x32_bf16 v[36:39], v[210:213], v[166:169], v[36:39]
	v_mfma_f32_16x16x32_bf16 v[28:31], v[202:205], v[174:177], v[28:31]
	v_mfma_f32_16x16x32_bf16 v[20:23], v[210:213], v[174:177], v[20:23]
	v_mfma_f32_16x16x32_bf16 v[12:15], v[202:205], v[186:189], v[12:15]
	v_mfma_f32_16x16x32_bf16 v[8:11], v[210:213], v[186:189], v[8:11]
	v_mfma_f32_16x16x32_bf16 v[4:7], v[202:205], v[194:197], v[4:7]
	v_mfma_f32_16x16x32_bf16 v[0:3], v[210:213], v[194:197], v[0:3]
	v_mfma_f32_16x16x32_bf16 v[44:47], v[206:209], v[170:173], v[44:47]
	v_mfma_f32_16x16x32_bf16 v[36:39], v[214:217], v[170:173], v[36:39]
	v_mfma_f32_16x16x32_bf16 v[28:31], v[206:209], v[178:181], v[28:31]
	v_mfma_f32_16x16x32_bf16 v[20:23], v[214:217], v[178:181], v[20:23]
	v_mfma_f32_16x16x32_bf16 v[12:15], v[206:209], v[190:193], v[12:15]
	v_mfma_f32_16x16x32_bf16 v[8:11], v[214:217], v[190:193], v[8:11]
	v_mfma_f32_16x16x32_bf16 v[4:7], v[206:209], v[198:201], v[4:7]
	v_mfma_f32_16x16x32_bf16 v[0:3], v[214:217], v[198:201], v[0:3]
	s_setprio 0
	s_add_u32 s6, s6, 0x100
	s_addc_u32 s7, s7, 0
	s_add_u32 s29, s29, 0x100
	s_addc_u32 s67, s67, 0
	s_cmp_ge_u32 s68, s66
	s_mov_b32 s24, s68
	s_barrier
	s_cbranch_scc0 .LBB0_1915
	s_lshl_b32 s24, s65, 8
	s_add_i32 s24, s24, s44
	v_or_b32_e32 v138, s24, v152
	v_lshl_or_b32 v142, s64, 8, v154
	s_cmp_gt_i32 s8, -1
	v_add_u32_e32 v140, 0xffffe000, v138
	s_mov_b64 s[6:7], -1
	s_cbranch_scc1 .LBB0_1950
	v_cmp_gt_i32_e32 vcc, s41, v138
	v_cmp_lt_i32_e64 s[6:7], s50, v138
	s_and_saveexec_b64 s[26:27], s[6:7]
	s_xor_b64 s[6:7], exec, s[26:27]
	v_mov_b32_e32 v141, v133
	v_lshlrev_b64 v[144:145], 13, v[140:141]
	v_mov_b32_e32 v139, v133
	v_lshl_add_u64 v[148:149], s[12:13], 0, v[144:145]
	v_lshlrev_b64 v[146:147], 13, v[138:139]
	s_andn2_saveexec_b64 s[6:7], s[6:7]
	v_ashrrev_i32_e32 v139, 31, v138
	v_lshlrev_b64 v[146:147], 13, v[138:139]
	v_lshl_add_u64 v[148:149], s[10:11], 0, v[146:147]
	s_or_b64 exec, exec, s[6:7]
	s_ashr_i32 s24, s24, 11
	v_lshrrev_b32_e32 v132, 2, v140
	v_or_b32_e32 v132, 4, v132
	v_mov_b32_e32 v139, s24
	v_cndmask_b32_e32 v132, v132, v139, vcc
	v_mov_b64_e32 v[144:145], s[14:15]
	v_ashrrev_i32_e32 v143, 31, v142
	v_mad_i64_i32 v[158:159], s[6:7], v132, s48, v[144:145]
	v_lshlrev_b64 v[144:145], 2, v[142:143]
	v_lshl_add_u64 v[166:167], v[148:149], 0, v[144:145]
	v_lshl_add_u64 v[158:159], v[158:159], 0, v[144:145]
	global_load_dwordx4 v[186:189], v[166:167], off
	global_load_dwordx4 v[202:205], v[158:159], off
	global_load_dwordx4 v[190:193], v[166:167], off offset:64
	global_load_dwordx4 v[206:209], v[158:159], off offset:64
	global_load_dwordx4 v[194:197], v[166:167], off offset:512
	global_load_dwordx4 v[210:213], v[158:159], off offset:512
	global_load_dwordx4 v[198:201], v[166:167], off offset:576
	global_load_dwordx4 v[214:217], v[158:159], off offset:576
	v_lshl_add_u64 v[146:147], s[10:11], 0, v[146:147]
	v_lshl_add_u64 v[168:169], v[146:147], 0, v[144:145]
	v_add_u32_e32 v132, 0xffffe010, v138
	s_waitcnt vmcnt(6)
	v_pk_fma_f32 v[188:189], v[126:127], v[204:205], v[188:189]
	v_pk_fma_f32 v[186:187], v[124:125], v[202:203], v[186:187]
	global_store_dwordx4 v[168:169], v[186:189], off
	v_or_b32_e32 v150, 16, v138
	v_cmp_gt_i32_e32 vcc, s41, v150
	v_cmp_lt_i32_e64 s[6:7], s50, v150
	s_waitcnt vmcnt(5)
	v_pk_fma_f32 v[192:193], v[122:123], v[208:209], v[192:193]
	v_pk_fma_f32 v[190:191], v[120:121], v[206:207], v[190:191]
	global_store_dwordx4 v[168:169], v[190:193], off offset:64
	s_waitcnt vmcnt(4)
	v_pk_fma_f32 v[196:197], v[110:111], v[212:213], v[196:197]
	v_pk_fma_f32 v[194:195], v[108:109], v[210:211], v[194:195]
	global_store_dwordx4 v[168:169], v[194:197], off offset:512
	s_waitcnt vmcnt(3)
;     __device__ __forceinline__ void operator()(const Acc& acc, const Unit& u, int wr, int wc, int fr, int fq) const {
;     ...
;             for (int m = 0; m < 4; ++m) { const int row = row0 + ai * HALF + m * 16; const int b = bidx_of_row(row);
;                 const float* xr = (row < TP) ? x0p + (size_t)row * DM : x0s + (size_t)(row - TP) * DM; const float* gr = gate + (size_t)b * MODW; float* orow = X1 + (size_t)row * DM;
; #pragma unroll
;                 for (int bj = 0; bj < 2; ++bj)
; #pragma unroll
;                     for (int n = 0; n < 2; ++n) { const int c = col0 + bj * HALF + n * 16; const f32x4 xv = *(const f32x4*)(xr + c), gv = *(const f32x4*)(gr + c);
;                         *(f32x4*)(orow + c) = xv + gv * acc[ai][bj][m][n]; } }
	v_pk_fma_f32 v[200:201], v[102:103], v[216:217], v[200:201]
	v_pk_fma_f32 v[198:199], v[100:101], v[214:215], v[198:199]
	global_store_dwordx4 v[168:169], v[198:201], off offset:576
	s_and_saveexec_b64 s[26:27], s[6:7]
	s_xor_b64 s[6:7], exec, s[26:27]
	v_lshlrev_b64 v[146:147], 13, v[132:133]
	v_mov_b32_e32 v151, v133
	v_lshl_add_u64 v[148:149], s[12:13], 0, v[146:147]
	v_lshlrev_b64 v[146:147], 13, v[150:151]
	s_andn2_saveexec_b64 s[6:7], s[6:7]
	v_ashrrev_i32_e32 v151, 31, v150
	v_lshlrev_b64 v[146:147], 13, v[150:151]
	v_lshl_add_u64 v[148:149], s[10:11], 0, v[146:147]
	s_or_b64 exec, exec, s[6:7]
	v_lshrrev_b32_e32 v132, 2, v132
	v_add_u32_e32 v132, 4, v132
	v_mov_b32_e32 v139, s24
	v_cndmask_b32_e32 v132, v132, v139, vcc
	v_mov_b64_e32 v[150:151], s[14:15]
	v_mad_i64_i32 v[158:159], s[6:7], v132, s48, v[150:151]
	v_lshl_add_u64 v[166:167], v[148:149], 0, v[144:145]
	v_lshl_add_u64 v[158:159], v[158:159], 0, v[144:145]
	global_load_dwordx4 v[186:189], v[166:167], off
	global_load_dwordx4 v[202:205], v[158:159], off
	global_load_dwordx4 v[190:193], v[166:167], off offset:64
	global_load_dwordx4 v[206:209], v[158:159], off offset:64
	global_load_dwordx4 v[194:197], v[166:167], off offset:512
	global_load_dwordx4 v[210:213], v[158:159], off offset:512
	global_load_dwordx4 v[198:201], v[166:167], off offset:576
	global_load_dwordx4 v[214:217], v[158:159], off offset:576
	v_lshl_add_u64 v[146:147], s[10:11], 0, v[146:147]
	v_lshl_add_u64 v[168:169], v[146:147], 0, v[144:145]
	v_add_u32_e32 v132, 0xffffe020, v138
	s_waitcnt vmcnt(6)
	v_pk_fma_f32 v[188:189], v[118:119], v[204:205], v[188:189]
	v_pk_fma_f32 v[186:187], v[116:117], v[202:203], v[186:187]
	global_store_dwordx4 v[168:169], v[186:189], off
	v_or_b32_e32 v150, 32, v138
	v_cmp_gt_i32_e32 vcc, s41, v150
	v_cmp_lt_i32_e64 s[6:7], s50, v150
	s_waitcnt vmcnt(5)
	v_pk_fma_f32 v[192:193], v[114:115], v[208:209], v[192:193]
	v_pk_fma_f32 v[190:191], v[112:113], v[206:207], v[190:191]
	global_store_dwordx4 v[168:169], v[190:193], off offset:64
	s_waitcnt vmcnt(4)
	v_pk_fma_f32 v[196:197], v[94:95], v[212:213], v[196:197]
	v_pk_fma_f32 v[194:195], v[92:93], v[210:211], v[194:195]
	global_store_dwordx4 v[168:169], v[194:197], off offset:512
	s_waitcnt vmcnt(3)
	v_pk_fma_f32 v[200:201], v[86:87], v[216:217], v[200:201]
	v_pk_fma_f32 v[198:199], v[84:85], v[214:215], v[198:199]
	global_store_dwordx4 v[168:169], v[198:201], off offset:576
	s_and_saveexec_b64 s[26:27], s[6:7]
	s_xor_b64 s[6:7], exec, s[26:27]
	v_lshlrev_b64 v[146:147], 13, v[132:133]
	v_mov_b32_e32 v151, v133
	v_lshl_add_u64 v[148:149], s[12:13], 0, v[146:147]
	v_lshlrev_b64 v[146:147], 13, v[150:151]
	s_andn2_saveexec_b64 s[6:7], s[6:7]
	v_ashrrev_i32_e32 v151, 31, v150
	v_lshlrev_b64 v[146:147], 13, v[150:151]
	v_lshl_add_u64 v[148:149], s[10:11], 0, v[146:147]
	s_or_b64 exec, exec, s[6:7]
	v_lshrrev_b32_e32 v132, 2, v132
	v_or_b32_e32 v132, 4, v132
	v_mov_b32_e32 v139, s24
	v_cndmask_b32_e32 v132, v132, v139, vcc
	v_mov_b64_e32 v[150:151], s[14:15]
	v_mad_i64_i32 v[158:159], s[6:7], v132, s48, v[150:151]
	v_lshl_add_u64 v[166:167], v[148:149], 0, v[144:145]
	v_lshl_add_u64 v[158:159], v[158:159], 0, v[144:145]
	global_load_dwordx4 v[186:189], v[166:167], off
	global_load_dwordx4 v[202:205], v[158:159], off
	global_load_dwordx4 v[190:193], v[166:167], off offset:64
	global_load_dwordx4 v[206:209], v[158:159], off offset:64
	global_load_dwordx4 v[194:197], v[166:167], off offset:512
	global_load_dwordx4 v[210:213], v[158:159], off offset:512
	global_load_dwordx4 v[198:201], v[166:167], off offset:576
	global_load_dwordx4 v[214:217], v[158:159], off offset:576
	v_lshl_add_u64 v[146:147], s[10:11], 0, v[146:147]
	v_lshl_add_u64 v[168:169], v[146:147], 0, v[144:145]
	v_add_u32_e32 v132, 0xffffe030, v138
	s_waitcnt vmcnt(6)
	v_pk_fma_f32 v[188:189], v[106:107], v[204:205], v[188:189]
	v_pk_fma_f32 v[186:187], v[104:105], v[202:203], v[186:187]
	global_store_dwordx4 v[168:169], v[186:189], off
	v_or_b32_e32 v150, 48, v138
	v_cmp_gt_i32_e32 vcc, s41, v150
	v_cmp_lt_i32_e64 s[6:7], s50, v150
	s_waitcnt vmcnt(5)
	v_pk_fma_f32 v[192:193], v[98:99], v[208:209], v[192:193]
	v_pk_fma_f32 v[190:191], v[96:97], v[206:207], v[190:191]
	global_store_dwordx4 v[168:169], v[190:193], off offset:64
	s_waitcnt vmcnt(4)
	v_pk_fma_f32 v[196:197], v[78:79], v[212:213], v[196:197]
	v_pk_fma_f32 v[194:195], v[76:77], v[210:211], v[194:195]
	global_store_dwordx4 v[168:169], v[194:197], off offset:512
	s_waitcnt vmcnt(3)
	v_pk_fma_f32 v[200:201], v[74:75], v[216:217], v[200:201]
	v_pk_fma_f32 v[198:199], v[72:73], v[214:215], v[198:199]
	global_store_dwordx4 v[168:169], v[198:201], off offset:576
	s_and_saveexec_b64 s[26:27], s[6:7]
	s_xor_b64 s[6:7], exec, s[26:27]
	v_lshlrev_b64 v[146:147], 13, v[132:133]
	v_mov_b32_e32 v151, v133
	v_lshl_add_u64 v[148:149], s[12:13], 0, v[146:147]
	v_lshlrev_b64 v[146:147], 13, v[150:151]
	s_andn2_saveexec_b64 s[6:7], s[6:7]
	v_ashrrev_i32_e32 v151, 31, v150
	v_lshlrev_b64 v[146:147], 13, v[150:151]
	v_lshl_add_u64 v[148:149], s[10:11], 0, v[146:147]
	s_or_b64 exec, exec, s[6:7]
	v_lshrrev_b32_e32 v132, 2, v132
	v_add_u32_e32 v132, 4, v132
	v_mov_b32_e32 v139, s24
	v_cndmask_b32_e32 v132, v132, v139, vcc
	v_mov_b64_e32 v[150:151], s[14:15]
	v_mad_i64_i32 v[158:159], s[6:7], v132, s48, v[150:151]
	v_lshl_add_u64 v[166:167], v[148:149], 0, v[144:145]
	v_lshl_add_u64 v[158:159], v[158:159], 0, v[144:145]
	global_load_dwordx4 v[186:189], v[166:167], off
	global_load_dwordx4 v[202:205], v[158:159], off
	global_load_dwordx4 v[190:193], v[166:167], off offset:64
	global_load_dwordx4 v[206:209], v[158:159], off offset:64
	global_load_dwordx4 v[194:197], v[166:167], off offset:512
	global_load_dwordx4 v[210:213], v[158:159], off offset:512
	global_load_dwordx4 v[198:201], v[166:167], off offset:576
	global_load_dwordx4 v[214:217], v[158:159], off offset:576
	v_lshl_add_u64 v[146:147], s[10:11], 0, v[146:147]
	v_lshl_add_u64 v[168:169], v[146:147], 0, v[144:145]
	v_cmp_gt_i32_e32 vcc, s51, v138
	v_cmp_lt_i32_e64 s[6:7], s52, v138
	v_add_u32_e32 v132, 0xffffe080, v138
	s_waitcnt vmcnt(6)
;     __device__ __forceinline__ void operator()(const Acc& acc, const Unit& u, int wr, int wc, int fr, int fq) const {
;     ...
;             for (int m = 0; m < 4; ++m) { const int row = row0 + ai * HALF + m * 16; const int b = bidx_of_row(row);
;                 const float* xr = (row < TP) ? x0p + (size_t)row * DM : x0s + (size_t)(row - TP) * DM; const float* gr = gate + (size_t)b * MODW; float* orow = X1 + (size_t)row * DM;
; #pragma unroll
;                 for (int bj = 0; bj < 2; ++bj)
; #pragma unroll
;                     for (int n = 0; n < 2; ++n) { const int c = col0 + bj * HALF + n * 16; const f32x4 xv = *(const f32x4*)(xr + c), gv = *(const f32x4*)(gr + c);
;                         *(f32x4*)(orow + c) = xv + gv * acc[ai][bj][m][n]; } }
	v_pk_fma_f32 v[188:189], v[90:91], v[204:205], v[188:189]
	v_pk_fma_f32 v[186:187], v[88:89], v[202:203], v[186:187]
	global_store_dwordx4 v[168:169], v[186:189], off
	s_waitcnt vmcnt(5)
	v_pk_fma_f32 v[192:193], v[82:83], v[208:209], v[192:193]
	v_pk_fma_f32 v[190:191], v[80:81], v[206:207], v[190:191]
	global_store_dwordx4 v[168:169], v[190:193], off offset:64
	s_waitcnt vmcnt(4)
	v_pk_fma_f32 v[196:197], v[70:71], v[212:213], v[196:197]
	v_pk_fma_f32 v[194:195], v[68:69], v[210:211], v[194:195]
	global_store_dwordx4 v[168:169], v[194:197], off offset:512
	v_add_u32_e32 v146, 0x80, v138
	s_waitcnt vmcnt(3)
	v_pk_fma_f32 v[200:201], v[66:67], v[216:217], v[200:201]
	v_pk_fma_f32 v[198:199], v[64:65], v[214:215], v[198:199]
	global_store_dwordx4 v[168:169], v[198:201], off offset:576
	s_and_saveexec_b64 s[24:25], s[6:7]
	s_xor_b64 s[6:7], exec, s[24:25]
	v_lshlrev_b64 v[148:149], 13, v[132:133]
	v_mov_b32_e32 v147, v133
	v_lshl_add_u64 v[150:151], s[12:13], 0, v[148:149]
	v_lshlrev_b64 v[148:149], 13, v[146:147]
	s_andn2_saveexec_b64 s[6:7], s[6:7]
	v_ashrrev_i32_e32 v147, 31, v146
	v_lshlrev_b64 v[148:149], 13, v[146:147]
	v_lshl_add_u64 v[150:151], s[10:11], 0, v[148:149]
	s_or_b64 exec, exec, s[6:7]
	v_lshrrev_b32_e32 v132, 2, v132
	v_ashrrev_i32_e32 v139, 11, v146
	v_or_b32_e32 v132, 4, v132
	v_cndmask_b32_e32 v132, v132, v139, vcc
	v_mov_b64_e32 v[146:147], s[14:15]
	v_mad_i64_i32 v[146:147], s[6:7], v132, s48, v[146:147]
	v_lshl_add_u64 v[150:151], v[150:151], 0, v[144:145]
	v_lshl_add_u64 v[158:159], v[146:147], 0, v[144:145]
	global_load_dwordx4 v[186:189], v[150:151], off
	global_load_dwordx4 v[202:205], v[158:159], off
	global_load_dwordx4 v[190:193], v[150:151], off offset:64
	global_load_dwordx4 v[206:209], v[158:159], off offset:64
	global_load_dwordx4 v[194:197], v[150:151], off offset:512
	global_load_dwordx4 v[210:213], v[158:159], off offset:512
	global_load_dwordx4 v[198:201], v[150:151], off offset:576
	global_load_dwordx4 v[214:217], v[158:159], off offset:576
	v_lshl_add_u64 v[146:147], s[10:11], 0, v[148:149]
	v_lshl_add_u64 v[170:171], v[146:147], 0, v[144:145]
	v_cmp_gt_i32_e32 vcc, s53, v138
	v_cmp_lt_i32_e64 s[6:7], s54, v138
	v_add_u32_e32 v132, 0xffffe090, v138
	s_waitcnt vmcnt(6)
	v_pk_fma_f32 v[148:149], v[62:63], v[204:205], v[188:189]
	v_pk_fma_f32 v[146:147], v[60:61], v[202:203], v[186:187]
	global_store_dwordx4 v[170:171], v[146:149], off
	s_waitcnt vmcnt(5)
	v_pk_fma_f32 v[192:193], v[58:59], v[208:209], v[192:193]
	v_pk_fma_f32 v[190:191], v[56:57], v[206:207], v[190:191]
	global_store_dwordx4 v[170:171], v[190:193], off offset:64
	s_waitcnt vmcnt(4)
	v_pk_fma_f32 v[196:197], v[46:47], v[212:213], v[196:197]
	v_pk_fma_f32 v[194:195], v[44:45], v[210:211], v[194:195]
	global_store_dwordx4 v[170:171], v[194:197], off offset:512
	v_add_u32_e32 v150, 0x90, v138
	s_waitcnt vmcnt(3)
	v_pk_fma_f32 v[200:201], v[38:39], v[216:217], v[200:201]
	v_pk_fma_f32 v[198:199], v[36:37], v[214:215], v[198:199]
	global_store_dwordx4 v[170:171], v[198:201], off offset:576
	s_and_saveexec_b64 s[24:25], s[6:7]
	s_xor_b64 s[6:7], exec, s[24:25]
	v_lshlrev_b64 v[146:147], 13, v[132:133]
	v_mov_b32_e32 v151, v133
	v_lshl_add_u64 v[148:149], s[12:13], 0, v[146:147]
	v_lshlrev_b64 v[146:147], 13, v[150:151]
	s_andn2_saveexec_b64 s[6:7], s[6:7]
	v_ashrrev_i32_e32 v151, 31, v150
	v_lshlrev_b64 v[146:147], 13, v[150:151]
	v_lshl_add_u64 v[148:149], s[10:11], 0, v[146:147]
	s_or_b64 exec, exec, s[6:7]
	v_lshrrev_b32_e32 v132, 2, v132
	v_add_u32_e32 v132, 4, v132
	v_cndmask_b32_e32 v132, v132, v139, vcc
	v_mov_b64_e32 v[150:151], s[14:15]
	v_mad_i64_i32 v[158:159], s[6:7], v132, s48, v[150:151]
	v_lshl_add_u64 v[166:167], v[148:149], 0, v[144:145]
	v_lshl_add_u64 v[158:159], v[158:159], 0, v[144:145]
	global_load_dwordx4 v[186:189], v[166:167], off
	global_load_dwordx4 v[202:205], v[158:159], off
	global_load_dwordx4 v[190:193], v[166:167], off offset:64
	global_load_dwordx4 v[206:209], v[158:159], off offset:64
	global_load_dwordx4 v[194:197], v[166:167], off offset:512
	global_load_dwordx4 v[210:213], v[158:159], off offset:512
	global_load_dwordx4 v[198:201], v[166:167], off offset:576
	global_load_dwordx4 v[214:217], v[158:159], off offset:576
	v_lshl_add_u64 v[146:147], s[10:11], 0, v[146:147]
	v_lshl_add_u64 v[168:169], v[146:147], 0, v[144:145]
	v_cmp_gt_i32_e32 vcc, s55, v138
	v_cmp_lt_i32_e64 s[6:7], s56, v138
	v_add_u32_e32 v132, 0xffffe0a0, v138
	s_waitcnt vmcnt(6)
	v_pk_fma_f32 v[188:189], v[54:55], v[204:205], v[188:189]
	v_pk_fma_f32 v[186:187], v[52:53], v[202:203], v[186:187]
	global_store_dwordx4 v[168:169], v[186:189], off
	v_add_u32_e32 v150, 0xa0, v138
	s_waitcnt vmcnt(5)
;     __device__ __forceinline__ void operator()(const Acc& acc, const Unit& u, int wr, int wc, int fr, int fq) const {
;     ...
;             for (int m = 0; m < 4; ++m) { const int row = row0 + ai * HALF + m * 16; const int b = bidx_of_row(row);
;                 const float* xr = (row < TP) ? x0p + (size_t)row * DM : x0s + (size_t)(row - TP) * DM; const float* gr = gate + (size_t)b * MODW; float* orow = X1 + (size_t)row * DM;
; #pragma unroll
;                 for (int bj = 0; bj < 2; ++bj)
; #pragma unroll
;                     for (int n = 0; n < 2; ++n) { const int c = col0 + bj * HALF + n * 16; const f32x4 xv = *(const f32x4*)(xr + c), gv = *(const f32x4*)(gr + c);
;                         *(f32x4*)(orow + c) = xv + gv * acc[ai][bj][m][n]; } }
	v_pk_fma_f32 v[192:193], v[50:51], v[208:209], v[192:193]
	v_pk_fma_f32 v[190:191], v[48:49], v[206:207], v[190:191]
	global_store_dwordx4 v[168:169], v[190:193], off offset:64
	s_waitcnt vmcnt(4)
	v_pk_fma_f32 v[196:197], v[30:31], v[212:213], v[196:197]
	v_pk_fma_f32 v[194:195], v[28:29], v[210:211], v[194:195]
	global_store_dwordx4 v[168:169], v[194:197], off offset:512
	s_waitcnt vmcnt(3)
	v_pk_fma_f32 v[200:201], v[22:23], v[216:217], v[200:201]
	v_pk_fma_f32 v[198:199], v[20:21], v[214:215], v[198:199]
	global_store_dwordx4 v[168:169], v[198:201], off offset:576
	s_and_saveexec_b64 s[24:25], s[6:7]
	s_xor_b64 s[6:7], exec, s[24:25]
	v_lshlrev_b64 v[146:147], 13, v[132:133]
	v_mov_b32_e32 v151, v133
	v_lshl_add_u64 v[148:149], s[12:13], 0, v[146:147]
	v_lshlrev_b64 v[146:147], 13, v[150:151]
	s_andn2_saveexec_b64 s[6:7], s[6:7]
	v_ashrrev_i32_e32 v151, 31, v150
	v_lshlrev_b64 v[146:147], 13, v[150:151]
	v_lshl_add_u64 v[148:149], s[10:11], 0, v[146:147]
	s_or_b64 exec, exec, s[6:7]
	v_lshrrev_b32_e32 v132, 2, v132
	v_or_b32_e32 v132, 4, v132
	v_cndmask_b32_e32 v132, v132, v139, vcc
	v_mov_b64_e32 v[150:151], s[14:15]
	v_mad_i64_i32 v[158:159], s[6:7], v132, s48, v[150:151]
	v_lshl_add_u64 v[166:167], v[148:149], 0, v[144:145]
	v_lshl_add_u64 v[158:159], v[158:159], 0, v[144:145]
	global_load_dwordx4 v[186:189], v[166:167], off
	global_load_dwordx4 v[202:205], v[158:159], off
	global_load_dwordx4 v[190:193], v[166:167], off offset:64
	global_load_dwordx4 v[206:209], v[158:159], off offset:64
	global_load_dwordx4 v[194:197], v[166:167], off offset:512
	global_load_dwordx4 v[210:213], v[158:159], off offset:512
	global_load_dwordx4 v[198:201], v[166:167], off offset:576
	global_load_dwordx4 v[214:217], v[158:159], off offset:576
	v_lshl_add_u64 v[146:147], s[10:11], 0, v[146:147]
	v_lshl_add_u64 v[168:169], v[146:147], 0, v[144:145]
	v_cmp_gt_i32_e32 vcc, s57, v138
	v_cmp_lt_i32_e64 s[6:7], s58, v138
	v_add_u32_e32 v132, 0xffffe0b0, v138
	s_waitcnt vmcnt(6)
	v_pk_fma_f32 v[188:189], v[42:43], v[204:205], v[188:189]
	v_pk_fma_f32 v[186:187], v[40:41], v[202:203], v[186:187]
	global_store_dwordx4 v[168:169], v[186:189], off
	v_add_u32_e32 v150, 0xb0, v138
	s_waitcnt vmcnt(5)
	v_pk_fma_f32 v[192:193], v[34:35], v[208:209], v[192:193]
	v_pk_fma_f32 v[190:191], v[32:33], v[206:207], v[190:191]
	global_store_dwordx4 v[168:169], v[190:193], off offset:64
	s_waitcnt vmcnt(4)
	v_pk_fma_f32 v[196:197], v[14:15], v[212:213], v[196:197]
	v_pk_fma_f32 v[194:195], v[12:13], v[210:211], v[194:195]
	global_store_dwordx4 v[168:169], v[194:197], off offset:512
	s_waitcnt vmcnt(3)
	v_pk_fma_f32 v[200:201], v[10:11], v[216:217], v[200:201]
	v_pk_fma_f32 v[198:199], v[8:9], v[214:215], v[198:199]
	global_store_dwordx4 v[168:169], v[198:201], off offset:576
	s_and_saveexec_b64 s[24:25], s[6:7]
	s_xor_b64 s[6:7], exec, s[24:25]
	v_lshlrev_b64 v[146:147], 13, v[132:133]
	v_mov_b32_e32 v151, v133
	v_lshl_add_u64 v[148:149], s[12:13], 0, v[146:147]
	v_lshlrev_b64 v[146:147], 13, v[150:151]
	s_andn2_saveexec_b64 s[6:7], s[6:7]
	v_ashrrev_i32_e32 v151, 31, v150
	v_lshlrev_b64 v[146:147], 13, v[150:151]
	v_lshl_add_u64 v[148:149], s[10:11], 0, v[146:147]
	s_or_b64 exec, exec, s[6:7]
	v_lshrrev_b32_e32 v132, 2, v132
	v_add_u32_e32 v132, 4, v132
	v_cndmask_b32_e32 v132, v132, v139, vcc
	v_mov_b64_e32 v[150:151], s[14:15]
	v_mad_i64_i32 v[158:159], s[6:7], v132, s48, v[150:151]
	v_lshl_add_u64 v[166:167], v[148:149], 0, v[144:145]
	v_lshl_add_u64 v[158:159], v[158:159], 0, v[144:145]
	global_load_dwordx4 v[186:189], v[166:167], off
	global_load_dwordx4 v[202:205], v[158:159], off
	global_load_dwordx4 v[190:193], v[166:167], off offset:64
	global_load_dwordx4 v[206:209], v[158:159], off offset:64
	global_load_dwordx4 v[194:197], v[166:167], off offset:512
	global_load_dwordx4 v[210:213], v[158:159], off offset:512
	global_load_dwordx4 v[198:201], v[166:167], off offset:576
	global_load_dwordx4 v[214:217], v[158:159], off offset:576
	v_lshl_add_u64 v[146:147], s[10:11], 0, v[146:147]
	v_lshl_add_u64 v[168:169], v[146:147], 0, v[144:145]
	s_mov_b64 s[6:7], 0
	s_waitcnt vmcnt(6)
	v_pk_fma_f32 v[146:147], v[26:27], v[204:205], v[188:189]
	v_pk_fma_f32 v[144:145], v[24:25], v[202:203], v[186:187]
	global_store_dwordx4 v[168:169], v[144:147], off
	s_waitcnt vmcnt(5)
	v_pk_fma_f32 v[192:193], v[18:19], v[208:209], v[192:193]
	v_pk_fma_f32 v[190:191], v[16:17], v[206:207], v[190:191]
	global_store_dwordx4 v[168:169], v[190:193], off offset:64
	s_waitcnt vmcnt(4)
	v_pk_fma_f32 v[196:197], v[6:7], v[212:213], v[196:197]
	v_pk_fma_f32 v[194:195], v[4:5], v[210:211], v[194:195]
	global_store_dwordx4 v[168:169], v[194:197], off offset:512
	s_waitcnt vmcnt(3)
	v_pk_fma_f32 v[200:201], v[2:3], v[216:217], v[200:201]
	v_pk_fma_f32 v[198:199], v[0:1], v[214:215], v[198:199]
	global_store_dwordx4 v[168:169], v[198:201], off offset:576
